# in-projection epilogue fast path for the sample-row tiles (all five output kinds), bias quads loaded two row-group pairs ahead
# speedup vs baseline: 1.0082x; 1.0011x over previous
.LBB0_763:
	s_waitcnt lgkmcnt(0)
	s_add_u32 s4, s12, 0xb100000
	s_addc_u32 s5, s13, 0
	s_add_u32 s50, s12, 0x13200000
	s_addc_u32 s51, s13, 0
	s_add_u32 s52, s12, 0x23400000
	s_addc_u32 s53, s13, 0
	s_add_u32 s54, s12, 0x25500000
	s_addc_u32 s55, s13, 0
	v_readlane_b32 s3, v252, 26
	s_add_u32 s3, s14, s3
	s_addc_u32 s16, s15, 0
	s_add_u32 s44, s3, 0x10200000
	s_addc_u32 s45, s16, 0
	v_readlane_b32 s3, v252, 36
	s_add_u32 s3, s14, s3
	s_addc_u32 s16, s15, 0
	s_add_u32 s46, s3, 0x115c0000
	s_addc_u32 s47, s16, 0
	s_add_u32 s3, s14, s58
	s_addc_u32 s16, s15, 0
	s_add_u32 s37, s3, 0x105c0000
	s_addc_u32 s49, s16, 0
	s_add_u32 s33, s3, 0x10dc0000
	s_addc_u32 s74, s16, 0
	s_add_u32 s3, s14, s60
	s_addc_u32 s14, s15, 0
	s_add_u32 s84, s3, 0x117a0000
	s_addc_u32 s85, s14, 0
	v_lshl_or_b32 v0, s2, 8, v206
	s_add_u32 s65, s3, 0x11ba0000
	v_subrev_u32_e32 v182, s26, v0
	s_addc_u32 s66, s14, 0
	s_mov_b64 s[2:3], -1
	s_and_b64 vcc, exec, s[10:11]
	v_add_u32_e32 v181, s71, v208
	v_ashrrev_i32_e32 v183, 31, v182
	v_lshlrev_b32_e32 v184, 2, v164
	s_cbranch_vccz .LBB0_1093
	s_cmp_lt_u32 s35, 5
	s_cbranch_scc1 .Lfn_entry
	v_readlane_b32 s2, v252, 35
	s_add_u32 s2, s12, s2
	s_addc_u32 s3, s13, 0
	v_ashrrev_i32_e32 v1, 31, v0
	v_lshl_add_u64 v[0:1], v[0:1], 2, s[2:3]
	s_mov_b64 s[2:3], 0x500000
	v_lshl_add_u64 v[196:197], v[0:1], 0, s[2:3]
	ds_read_b128 v[0:3], v181
	s_cmp_eq_u32 s35, 2
	s_cselect_b32 s26, s85, s66
	s_cselect_b32 s27, s84, s65
	s_cselect_b32 s86, s49, s74
	s_waitcnt lgkmcnt(0)
	v_mov_b32_e32 v4, v1
	v_mov_b32_e32 v5, v2
	v_mov_b32_e32 v1, v3
	v_pk_add_f32 v[0:1], v[4:5], v[0:1]
	s_cselect_b32 s87, s37, s33
	v_add_f32_e32 v0, v0, v1
	v_fmamk_f32 v0, v0, 0x3a800000, v212
	v_cmp_gt_f32_e32 vcc, s59, v0
	v_mul_f32_e32 v1, 0x4b800000, v0
	s_lshl_b32 s88, s36, 8
	v_cndmask_b32_e32 v0, v0, v1, vcc
	v_rsq_f32_e32 v0, v0
	s_add_i32 s89, s88, s20
	s_add_i32 s3, s89, 0xffff0000
	s_lshr_b32 s90, s3, 5
	v_or_b32_e32 v6, s89, v163
	v_mul_f32_e32 v1, 0x45800000, v0
	s_ashr_i32 s2, s89, 11
	s_add_i32 s3, s90, 32
	v_cndmask_b32_e32 v146, v0, v1, vcc
	v_cmp_gt_i32_e64 s[10:11], s72, v6
	v_mov_b32_e32 v0, s3
	v_mov_b32_e32 v1, s2
	s_movk_i32 s12, 0xc00
	v_cndmask_b32_e64 v0, v0, v1, s[10:11]
	v_mul_lo_u32 v0, v0, s12
	s_lshl_b64 s[12:13], s[90:91], 17
	s_add_u32 s12, s27, s12
	v_ashrrev_i32_e32 v1, 31, v0
	s_addc_u32 s13, s26, s13
	v_mov_b32_e32 v185, v97
	s_movk_i32 s14, 0x77f
	v_lshl_add_u64 v[148:149], v[0:1], 2, v[196:197]
	v_bitop3_b32 v2, s89, v217, v163 bitop3:0xc8
	v_lshl_add_u64 v[0:1], s[12:13], 0, v[184:185]
	s_mov_b64 s[12:13], 0x18000
	s_ashr_i32 s3, s2, 31
	v_lshl_add_u64 v[186:187], v[0:1], 0, s[12:13]
	v_cmp_lt_u32_e64 s[12:13], s14, v2
	s_lshl_b64 s[14:15], s[2:3], 17
	v_add_u32_e32 v96, 0xfffff880, v2
	s_add_u32 s18, s87, s14
	s_addc_u32 s19, s86, s15
	v_lshlrev_b64 v[0:1], 10, v[96:97]
	v_lshl_add_u64 v[188:189], s[18:19], 0, v[0:1]
	global_load_dwordx4 v[0:3], v[148:149], off offset:16
	global_load_dwordx4 v[4:7], v[148:149], off
	s_movk_i32 s69, 0xc00
	s_movk_i32 s76, 0x77f
	s_mov_b64 s[14:15], -1
	s_cmp_lt_i32 s35, 1
	s_waitcnt vmcnt(0)
	v_pk_fma_f32 v[2:3], v[132:133], v[146:147], v[2:3] op_sel_hi:[1,0,1]
	v_pk_fma_f32 v[6:7], v[136:137], v[146:147], v[6:7] op_sel_hi:[1,0,1]
	v_pk_fma_f32 v[4:5], v[134:135], v[146:147], v[4:5] op_sel_hi:[1,0,1]
	v_pk_fma_f32 v[0:1], v[130:131], v[146:147], v[0:1] op_sel_hi:[1,0,1]
	s_cbranch_scc1 .LBB0_774
	v_mov_b64_e32 v[140:141], v[6:7]
	v_mov_b64_e32 v[144:145], v[2:3]
	s_cmp_gt_i32 s35, 3
	v_mov_b64_e32 v[138:139], v[4:5]
	v_mov_b64_e32 v[142:143], v[0:1]
	s_cbranch_scc1 .LBB0_773
	s_cmp_lg_u32 s35, 1
	s_cbranch_scc0 .LBB0_770
	v_lshlrev_b64 v[138:139], 2, v[182:183]
	v_lshl_add_u64 v[140:141], v[186:187], 0, v[138:139]
	v_lshl_add_u64 v[138:139], v[188:189], 0, v[138:139]
	v_cndmask_b32_e64 v96, 0, v138, s[12:13]
	v_cndmask_b32_e64 v138, 0, v139, s[12:13]
	v_cndmask_b32_e64 v139, v141, v138, s[10:11]
	v_cndmask_b32_e64 v138, v140, v96, s[10:11]
	v_cmp_ne_u64_e32 vcc, 0, v[138:139]
	s_and_saveexec_b64 s[14:15], vcc
	s_cbranch_execz .LBB0_769
	global_store_dwordx4 v[138:139], v[4:7], off
	global_store_dwordx4 v[138:139], v[0:3], off offset:16

.Lfn_entry:
	v_add_u32_e32 v1, s71, v208
	ds_read_b128 v[186:189], v1
	ds_read_b128 v[190:193], v1 offset:256
	ds_read_b128 v[194:197], v1 offset:512
	ds_read_b128 v[198:201], v1 offset:768
	ds_read_b128 v[202:205], v1 offset:2048
	ds_read_b128 v[222:225], v1 offset:2304
	ds_read_b128 v[226:229], v1 offset:2560
	ds_read_b128 v[230:233], v1 offset:2816
	s_sub_i32 s16, s36, 0x100
	s_lshl_b32 s16, s16, 8
	s_add_i32 s16, s16, s20
	s_lshr_b32 s17, s16, 5
	s_add_i32 s18, s17, 32
	s_mul_i32 s18, s18, 0x3000
	v_readlane_b32 s19, v252, 35
	s_add_u32 s10, s12, 0x500000
	s_addc_u32 s11, s13, 0
	s_add_u32 s10, s10, s19
	s_addc_u32 s11, s11, 0
	s_add_u32 s10, s10, s18
	s_addc_u32 s11, s11, 0
	v_lshlrev_b32_e32 v3, 2, v0
	global_load_dwordx4 v[150:153], v3, s[10:11]
	global_load_dwordx4 v[146:149], v3, s[10:11] offset:16
	global_load_dwordx4 v[142:145], v3, s[10:11] offset:128
	global_load_dwordx4 v[138:141], v3, s[10:11] offset:144
	s_waitcnt lgkmcnt(0)
	v_add_f32_e32 v4, v186, v187
	v_add_f32_e32 v5, v188, v189
	v_add_f32_e32 v4, v4, v5
	v_fmamk_f32 v4, v4, 0x3a800000, v212
	v_rsq_f32_e32 v186, v4
	v_add_f32_e32 v4, v190, v191
	v_add_f32_e32 v5, v192, v193
	v_add_f32_e32 v4, v4, v5
	v_fmamk_f32 v4, v4, 0x3a800000, v212
	v_rsq_f32_e32 v187, v4
	v_add_f32_e32 v4, v194, v195
	v_add_f32_e32 v5, v196, v197
	v_add_f32_e32 v4, v4, v5
	v_fmamk_f32 v4, v4, 0x3a800000, v212
	v_rsq_f32_e32 v188, v4
	v_add_f32_e32 v4, v198, v199
	v_add_f32_e32 v5, v200, v201
	v_add_f32_e32 v4, v4, v5
	v_fmamk_f32 v4, v4, 0x3a800000, v212
	v_rsq_f32_e32 v189, v4
	v_add_f32_e32 v4, v202, v203
	v_add_f32_e32 v5, v204, v205
	v_add_f32_e32 v4, v4, v5
	v_fmamk_f32 v4, v4, 0x3a800000, v212
	v_rsq_f32_e32 v190, v4
	v_add_f32_e32 v4, v222, v223
	v_add_f32_e32 v5, v224, v225
	v_add_f32_e32 v4, v4, v5
	v_fmamk_f32 v4, v4, 0x3a800000, v212
	v_rsq_f32_e32 v191, v4
	v_add_f32_e32 v4, v226, v227
	v_add_f32_e32 v5, v228, v229
	v_add_f32_e32 v4, v4, v5
	v_fmamk_f32 v4, v4, 0x3a800000, v212
	v_rsq_f32_e32 v192, v4
	v_add_f32_e32 v4, v230, v231
	v_add_f32_e32 v5, v232, v233
	v_add_f32_e32 v4, v4, v5
	v_fmamk_f32 v4, v4, 0x3a800000, v212
	v_rsq_f32_e32 v193, v4
	v_mov_b32_e32 v226, v3
	s_add_u32 s10, s10, 0x3000
	s_addc_u32 s11, s11, 0
	global_load_dwordx4 v[194:197], v226, s[10:11]
	global_load_dwordx4 v[198:201], v226, s[10:11] offset:16
	global_load_dwordx4 v[202:205], v226, s[10:11] offset:128
	global_load_dwordx4 v[222:225], v226, s[10:11] offset:144
	v_add_u32_e32 v2, v182, v162
	v_lshlrev_b32_e32 v2, 1, v2
	v_lshlrev_b32_e32 v227, 10, v163
	v_lshl_add_u32 v227, v182, 2, v227
	v_add_u32_e32 v228, -1, v163
	v_lshlrev_b32_e32 v228, 12, v228
	v_lshl_add_u32 v228, v182, 2, v228
	s_mov_b32 s17, s42
	s_add_i32 s18, s16, 0x10000
	v_readlane_b32 s2, v252, 28
	v_readlane_b32 s3, v252, 29
	s_cmp_gt_u32 s35, 1
	s_cbranch_scc1 .Lfn_k234
	v_lshl_add_u32 v246, v207, 11, v2
	v_add_u32_e32 v247, 0x4000, v246
	s_cmp_eq_u32 s35, 0
	s_cselect_b32 s12, s4, s50
	s_cselect_b32 s13, s5, s51
	s_lshl_b32 s18, s18, 11
	s_add_u32 s12, s12, s18
	s_addc_u32 s13, s13, 0
	s_mov_b32 s16, s42
	s_cmp_eq_u32 s35, 0
	s_cbranch_scc0 .Lfn_kind1
	s_cmp_eq_u32 s42, 1.0
	s_cbranch_scc1 .Lfn_plain
	s_waitcnt vmcnt(4)
	v_mov_b32_e32 v6, v186
	v_pk_fma_f32 v[136:137], v[136:137], v[6:7], v[152:153] op_sel_hi:[1,0,1]
	v_pk_fma_f32 v[134:135], v[134:135], v[6:7], v[150:151] op_sel_hi:[1,0,1]
	v_pk_fma_f32 v[132:133], v[132:133], v[6:7], v[148:149] op_sel_hi:[1,0,1]
	v_pk_fma_f32 v[130:131], v[130:131], v[6:7], v[146:147] op_sel_hi:[1,0,1]
	v_pk_fma_f32 v[128:129], v[128:129], v[6:7], v[144:145] op_sel_hi:[1,0,1]
	v_pk_fma_f32 v[126:127], v[126:127], v[6:7], v[142:143] op_sel_hi:[1,0,1]
	v_pk_fma_f32 v[124:125], v[124:125], v[6:7], v[140:141] op_sel_hi:[1,0,1]
	v_pk_fma_f32 v[122:123], v[122:123], v[6:7], v[138:139] op_sel_hi:[1,0,1]
	v_pk_mul_f32 v[136:137], s[16:17], v[136:137]
	v_pk_mul_f32 v[134:135], s[16:17], v[134:135]
	v_pk_mul_f32 v[132:133], s[16:17], v[132:133]
	v_pk_mul_f32 v[130:131], s[16:17], v[130:131]
	v_pk_mul_f32 v[128:129], s[16:17], v[128:129]
	v_pk_mul_f32 v[126:127], s[16:17], v[126:127]
	v_pk_mul_f32 v[124:125], s[16:17], v[124:125]
	v_pk_mul_f32 v[122:123], s[16:17], v[122:123]
	v_cvt_pk_bf16_f32 v234, v134, v135
	v_cvt_pk_bf16_f32 v235, v136, v137
	v_cvt_pk_bf16_f32 v236, v130, v131
	v_cvt_pk_bf16_f32 v237, v132, v133
	v_cvt_pk_bf16_f32 v238, v126, v127
	v_cvt_pk_bf16_f32 v239, v128, v129
	v_cvt_pk_bf16_f32 v240, v122, v123
	v_cvt_pk_bf16_f32 v241, v124, v125
	s_mov_b64 vcc, s[6:7]
	v_cndmask_b32_dpp v134, v238, v234, vcc row_ror:8 row_mask:0xf bank_mask:0xf
	v_cndmask_b32_dpp v135, v239, v235, vcc row_ror:8 row_mask:0xf bank_mask:0xf
	v_cndmask_b32_dpp v136, v240, v236, vcc row_ror:8 row_mask:0xf bank_mask:0xf
	v_cndmask_b32_dpp v137, v241, v237, vcc row_ror:8 row_mask:0xf bank_mask:0xf
	s_not_b64 vcc, s[6:7]
	v_cndmask_b32_dpp v130, v234, v238, vcc row_ror:8 row_mask:0xf bank_mask:0xf
	v_cndmask_b32_dpp v131, v235, v239, vcc row_ror:8 row_mask:0xf bank_mask:0xf
	v_cndmask_b32_dpp v132, v236, v240, vcc row_ror:8 row_mask:0xf bank_mask:0xf
	v_cndmask_b32_dpp v133, v237, v241, vcc row_ror:8 row_mask:0xf bank_mask:0xf
	global_store_dwordx4 v246, v[134:137], s[12:13]
	global_store_dwordx4 v247, v[130:133], s[12:13]
	v_mov_b32_e32 v6, v187
	s_add_u32 s12, s12, 0x8000
	s_addc_u32 s13, s13, 0
	v_pk_fma_f32 v[120:121], v[120:121], v[6:7], v[152:153] op_sel_hi:[1,0,1]
	v_pk_fma_f32 v[118:119], v[118:119], v[6:7], v[150:151] op_sel_hi:[1,0,1]
	v_pk_fma_f32 v[116:117], v[116:117], v[6:7], v[148:149] op_sel_hi:[1,0,1]
	v_pk_fma_f32 v[114:115], v[114:115], v[6:7], v[146:147] op_sel_hi:[1,0,1]
	v_pk_fma_f32 v[112:113], v[112:113], v[6:7], v[144:145] op_sel_hi:[1,0,1]
	v_pk_fma_f32 v[110:111], v[110:111], v[6:7], v[142:143] op_sel_hi:[1,0,1]
	v_pk_fma_f32 v[108:109], v[108:109], v[6:7], v[140:141] op_sel_hi:[1,0,1]
	v_pk_fma_f32 v[106:107], v[106:107], v[6:7], v[138:139] op_sel_hi:[1,0,1]
	v_pk_mul_f32 v[120:121], s[16:17], v[120:121]
	v_pk_mul_f32 v[118:119], s[16:17], v[118:119]
	v_pk_mul_f32 v[116:117], s[16:17], v[116:117]
	v_pk_mul_f32 v[114:115], s[16:17], v[114:115]
	v_pk_mul_f32 v[112:113], s[16:17], v[112:113]
	v_pk_mul_f32 v[110:111], s[16:17], v[110:111]
	v_pk_mul_f32 v[108:109], s[16:17], v[108:109]
	v_pk_mul_f32 v[106:107], s[16:17], v[106:107]
	v_cvt_pk_bf16_f32 v234, v118, v119
	v_cvt_pk_bf16_f32 v235, v120, v121
	v_cvt_pk_bf16_f32 v236, v114, v115
	v_cvt_pk_bf16_f32 v237, v116, v117
	v_cvt_pk_bf16_f32 v238, v110, v111
	v_cvt_pk_bf16_f32 v239, v112, v113
	v_cvt_pk_bf16_f32 v240, v106, v107
	v_cvt_pk_bf16_f32 v241, v108, v109
	s_mov_b64 vcc, s[6:7]
	v_cndmask_b32_dpp v118, v238, v234, vcc row_ror:8 row_mask:0xf bank_mask:0xf
	v_cndmask_b32_dpp v119, v239, v235, vcc row_ror:8 row_mask:0xf bank_mask:0xf
	v_cndmask_b32_dpp v120, v240, v236, vcc row_ror:8 row_mask:0xf bank_mask:0xf
	v_cndmask_b32_dpp v121, v241, v237, vcc row_ror:8 row_mask:0xf bank_mask:0xf
	s_not_b64 vcc, s[6:7]
	v_cndmask_b32_dpp v114, v234, v238, vcc row_ror:8 row_mask:0xf bank_mask:0xf
	v_cndmask_b32_dpp v115, v235, v239, vcc row_ror:8 row_mask:0xf bank_mask:0xf
	v_cndmask_b32_dpp v116, v236, v240, vcc row_ror:8 row_mask:0xf bank_mask:0xf
	v_cndmask_b32_dpp v117, v237, v241, vcc row_ror:8 row_mask:0xf bank_mask:0xf
	global_store_dwordx4 v246, v[118:121], s[12:13]
	global_store_dwordx4 v247, v[114:117], s[12:13]
	s_add_u32 s10, s10, 0x9000
	s_addc_u32 s11, s11, 0
	global_load_dwordx4 v[150:153], v226, s[10:11]
	global_load_dwordx4 v[146:149], v226, s[10:11] offset:16
	global_load_dwordx4 v[142:145], v226, s[10:11] offset:128
	global_load_dwordx4 v[138:141], v226, s[10:11] offset:144
	s_waitcnt vmcnt(8)
	v_mov_b32_e32 v6, v188
	s_add_u32 s12, s12, 0x8000
	s_addc_u32 s13, s13, 0
	v_pk_fma_f32 v[104:105], v[104:105], v[6:7], v[196:197] op_sel_hi:[1,0,1]
	v_pk_fma_f32 v[102:103], v[102:103], v[6:7], v[194:195] op_sel_hi:[1,0,1]
	v_pk_fma_f32 v[100:101], v[100:101], v[6:7], v[200:201] op_sel_hi:[1,0,1]
	v_pk_fma_f32 v[98:99], v[98:99], v[6:7], v[198:199] op_sel_hi:[1,0,1]
	v_pk_fma_f32 v[94:95], v[94:95], v[6:7], v[204:205] op_sel_hi:[1,0,1]
	v_pk_fma_f32 v[92:93], v[92:93], v[6:7], v[202:203] op_sel_hi:[1,0,1]
	v_pk_fma_f32 v[90:91], v[90:91], v[6:7], v[224:225] op_sel_hi:[1,0,1]
	v_pk_fma_f32 v[88:89], v[88:89], v[6:7], v[222:223] op_sel_hi:[1,0,1]
	v_pk_mul_f32 v[104:105], s[16:17], v[104:105]
	v_pk_mul_f32 v[102:103], s[16:17], v[102:103]
	v_pk_mul_f32 v[100:101], s[16:17], v[100:101]
	v_pk_mul_f32 v[98:99], s[16:17], v[98:99]
	v_pk_mul_f32 v[94:95], s[16:17], v[94:95]
	v_pk_mul_f32 v[92:93], s[16:17], v[92:93]
	v_pk_mul_f32 v[90:91], s[16:17], v[90:91]
	v_pk_mul_f32 v[88:89], s[16:17], v[88:89]
	v_cvt_pk_bf16_f32 v234, v102, v103
	v_cvt_pk_bf16_f32 v235, v104, v105
	v_cvt_pk_bf16_f32 v236, v98, v99
	v_cvt_pk_bf16_f32 v237, v100, v101
	v_cvt_pk_bf16_f32 v238, v92, v93
	v_cvt_pk_bf16_f32 v239, v94, v95
	v_cvt_pk_bf16_f32 v240, v88, v89
	v_cvt_pk_bf16_f32 v241, v90, v91
	s_mov_b64 vcc, s[6:7]
	v_cndmask_b32_dpp v102, v238, v234, vcc row_ror:8 row_mask:0xf bank_mask:0xf
	v_cndmask_b32_dpp v103, v239, v235, vcc row_ror:8 row_mask:0xf bank_mask:0xf
	v_cndmask_b32_dpp v104, v240, v236, vcc row_ror:8 row_mask:0xf bank_mask:0xf
	v_cndmask_b32_dpp v105, v241, v237, vcc row_ror:8 row_mask:0xf bank_mask:0xf
	s_not_b64 vcc, s[6:7]
	v_cndmask_b32_dpp v98, v234, v238, vcc row_ror:8 row_mask:0xf bank_mask:0xf
	v_cndmask_b32_dpp v99, v235, v239, vcc row_ror:8 row_mask:0xf bank_mask:0xf
	v_cndmask_b32_dpp v100, v236, v240, vcc row_ror:8 row_mask:0xf bank_mask:0xf
	v_cndmask_b32_dpp v101, v237, v241, vcc row_ror:8 row_mask:0xf bank_mask:0xf
	global_store_dwordx4 v246, v[102:105], s[12:13]
	global_store_dwordx4 v247, v[98:101], s[12:13]
	v_mov_b32_e32 v6, v189
	s_add_u32 s12, s12, 0x8000
	s_addc_u32 s13, s13, 0
	v_pk_fma_f32 v[86:87], v[86:87], v[6:7], v[196:197] op_sel_hi:[1,0,1]
	v_pk_fma_f32 v[84:85], v[84:85], v[6:7], v[194:195] op_sel_hi:[1,0,1]
	v_pk_fma_f32 v[82:83], v[82:83], v[6:7], v[200:201] op_sel_hi:[1,0,1]
	v_pk_fma_f32 v[80:81], v[80:81], v[6:7], v[198:199] op_sel_hi:[1,0,1]
	v_pk_fma_f32 v[78:79], v[78:79], v[6:7], v[204:205] op_sel_hi:[1,0,1]
	v_pk_fma_f32 v[76:77], v[76:77], v[6:7], v[202:203] op_sel_hi:[1,0,1]
	v_pk_fma_f32 v[74:75], v[74:75], v[6:7], v[224:225] op_sel_hi:[1,0,1]
	v_pk_fma_f32 v[72:73], v[72:73], v[6:7], v[222:223] op_sel_hi:[1,0,1]
	v_pk_mul_f32 v[86:87], s[16:17], v[86:87]
	v_pk_mul_f32 v[84:85], s[16:17], v[84:85]
	v_pk_mul_f32 v[82:83], s[16:17], v[82:83]
	v_pk_mul_f32 v[80:81], s[16:17], v[80:81]
	v_pk_mul_f32 v[78:79], s[16:17], v[78:79]
	v_pk_mul_f32 v[76:77], s[16:17], v[76:77]
	v_pk_mul_f32 v[74:75], s[16:17], v[74:75]
	v_pk_mul_f32 v[72:73], s[16:17], v[72:73]
	v_cvt_pk_bf16_f32 v234, v84, v85
	v_cvt_pk_bf16_f32 v235, v86, v87
	v_cvt_pk_bf16_f32 v236, v80, v81
	v_cvt_pk_bf16_f32 v237, v82, v83
	v_cvt_pk_bf16_f32 v238, v76, v77
	v_cvt_pk_bf16_f32 v239, v78, v79
	v_cvt_pk_bf16_f32 v240, v72, v73
	v_cvt_pk_bf16_f32 v241, v74, v75
	s_mov_b64 vcc, s[6:7]
	v_cndmask_b32_dpp v84, v238, v234, vcc row_ror:8 row_mask:0xf bank_mask:0xf
	v_cndmask_b32_dpp v85, v239, v235, vcc row_ror:8 row_mask:0xf bank_mask:0xf
	v_cndmask_b32_dpp v86, v240, v236, vcc row_ror:8 row_mask:0xf bank_mask:0xf
	v_cndmask_b32_dpp v87, v241, v237, vcc row_ror:8 row_mask:0xf bank_mask:0xf
	s_not_b64 vcc, s[6:7]
	v_cndmask_b32_dpp v80, v234, v238, vcc row_ror:8 row_mask:0xf bank_mask:0xf
	v_cndmask_b32_dpp v81, v235, v239, vcc row_ror:8 row_mask:0xf bank_mask:0xf
	v_cndmask_b32_dpp v82, v236, v240, vcc row_ror:8 row_mask:0xf bank_mask:0xf
	v_cndmask_b32_dpp v83, v237, v241, vcc row_ror:8 row_mask:0xf bank_mask:0xf
	global_store_dwordx4 v246, v[84:87], s[12:13]
	global_store_dwordx4 v247, v[80:83], s[12:13]
	s_add_u32 s10, s10, 0x3000
	s_addc_u32 s11, s11, 0
	global_load_dwordx4 v[194:197], v226, s[10:11]
	global_load_dwordx4 v[198:201], v226, s[10:11] offset:16
	global_load_dwordx4 v[202:205], v226, s[10:11] offset:128
	global_load_dwordx4 v[222:225], v226, s[10:11] offset:144
	s_waitcnt vmcnt(8)
	v_mov_b32_e32 v6, v190
	s_add_u32 s12, s12, 0x28000
	s_addc_u32 s13, s13, 0
	v_pk_fma_f32 v[70:71], v[70:71], v[6:7], v[152:153] op_sel_hi:[1,0,1]
	v_pk_fma_f32 v[68:69], v[68:69], v[6:7], v[150:151] op_sel_hi:[1,0,1]
	v_pk_fma_f32 v[66:67], v[66:67], v[6:7], v[148:149] op_sel_hi:[1,0,1]
	v_pk_fma_f32 v[64:65], v[64:65], v[6:7], v[146:147] op_sel_hi:[1,0,1]
	v_pk_fma_f32 v[62:63], v[62:63], v[6:7], v[144:145] op_sel_hi:[1,0,1]
	v_pk_fma_f32 v[60:61], v[60:61], v[6:7], v[142:143] op_sel_hi:[1,0,1]
	v_pk_fma_f32 v[58:59], v[58:59], v[6:7], v[140:141] op_sel_hi:[1,0,1]
	v_pk_fma_f32 v[56:57], v[56:57], v[6:7], v[138:139] op_sel_hi:[1,0,1]
	v_pk_mul_f32 v[70:71], s[16:17], v[70:71]
	v_pk_mul_f32 v[68:69], s[16:17], v[68:69]
	v_pk_mul_f32 v[66:67], s[16:17], v[66:67]
	v_pk_mul_f32 v[64:65], s[16:17], v[64:65]
	v_pk_mul_f32 v[62:63], s[16:17], v[62:63]
	v_pk_mul_f32 v[60:61], s[16:17], v[60:61]
	v_pk_mul_f32 v[58:59], s[16:17], v[58:59]
	v_pk_mul_f32 v[56:57], s[16:17], v[56:57]
	v_cvt_pk_bf16_f32 v234, v68, v69
	v_cvt_pk_bf16_f32 v235, v70, v71
	v_cvt_pk_bf16_f32 v236, v64, v65
	v_cvt_pk_bf16_f32 v237, v66, v67
	v_cvt_pk_bf16_f32 v238, v60, v61
	v_cvt_pk_bf16_f32 v239, v62, v63
	v_cvt_pk_bf16_f32 v240, v56, v57
	v_cvt_pk_bf16_f32 v241, v58, v59
	s_mov_b64 vcc, s[6:7]
	v_cndmask_b32_dpp v68, v238, v234, vcc row_ror:8 row_mask:0xf bank_mask:0xf
	v_cndmask_b32_dpp v69, v239, v235, vcc row_ror:8 row_mask:0xf bank_mask:0xf
	v_cndmask_b32_dpp v70, v240, v236, vcc row_ror:8 row_mask:0xf bank_mask:0xf
	v_cndmask_b32_dpp v71, v241, v237, vcc row_ror:8 row_mask:0xf bank_mask:0xf
	s_not_b64 vcc, s[6:7]
	v_cndmask_b32_dpp v64, v234, v238, vcc row_ror:8 row_mask:0xf bank_mask:0xf
	v_cndmask_b32_dpp v65, v235, v239, vcc row_ror:8 row_mask:0xf bank_mask:0xf
	v_cndmask_b32_dpp v66, v236, v240, vcc row_ror:8 row_mask:0xf bank_mask:0xf
	v_cndmask_b32_dpp v67, v237, v241, vcc row_ror:8 row_mask:0xf bank_mask:0xf
	global_store_dwordx4 v246, v[68:71], s[12:13]
	global_store_dwordx4 v247, v[64:67], s[12:13]
	v_mov_b32_e32 v6, v191
	s_add_u32 s12, s12, 0x8000
	s_addc_u32 s13, s13, 0
	v_pk_fma_f32 v[54:55], v[54:55], v[6:7], v[152:153] op_sel_hi:[1,0,1]
	v_pk_fma_f32 v[52:53], v[52:53], v[6:7], v[150:151] op_sel_hi:[1,0,1]
	v_pk_fma_f32 v[50:51], v[50:51], v[6:7], v[148:149] op_sel_hi:[1,0,1]
	v_pk_fma_f32 v[48:49], v[48:49], v[6:7], v[146:147] op_sel_hi:[1,0,1]
	v_pk_fma_f32 v[46:47], v[46:47], v[6:7], v[144:145] op_sel_hi:[1,0,1]
	v_pk_fma_f32 v[44:45], v[44:45], v[6:7], v[142:143] op_sel_hi:[1,0,1]
	v_pk_fma_f32 v[42:43], v[42:43], v[6:7], v[140:141] op_sel_hi:[1,0,1]
	v_pk_fma_f32 v[40:41], v[40:41], v[6:7], v[138:139] op_sel_hi:[1,0,1]
	v_pk_mul_f32 v[54:55], s[16:17], v[54:55]
	v_pk_mul_f32 v[52:53], s[16:17], v[52:53]
	v_pk_mul_f32 v[50:51], s[16:17], v[50:51]
	v_pk_mul_f32 v[48:49], s[16:17], v[48:49]
	v_pk_mul_f32 v[46:47], s[16:17], v[46:47]
	v_pk_mul_f32 v[44:45], s[16:17], v[44:45]
	v_pk_mul_f32 v[42:43], s[16:17], v[42:43]
	v_pk_mul_f32 v[40:41], s[16:17], v[40:41]
	v_cvt_pk_bf16_f32 v234, v52, v53
	v_cvt_pk_bf16_f32 v235, v54, v55
	v_cvt_pk_bf16_f32 v236, v48, v49
	v_cvt_pk_bf16_f32 v237, v50, v51
	v_cvt_pk_bf16_f32 v238, v44, v45
	v_cvt_pk_bf16_f32 v239, v46, v47
	v_cvt_pk_bf16_f32 v240, v40, v41
	v_cvt_pk_bf16_f32 v241, v42, v43
	s_mov_b64 vcc, s[6:7]
	v_cndmask_b32_dpp v52, v238, v234, vcc row_ror:8 row_mask:0xf bank_mask:0xf
	v_cndmask_b32_dpp v53, v239, v235, vcc row_ror:8 row_mask:0xf bank_mask:0xf
	v_cndmask_b32_dpp v54, v240, v236, vcc row_ror:8 row_mask:0xf bank_mask:0xf
	v_cndmask_b32_dpp v55, v241, v237, vcc row_ror:8 row_mask:0xf bank_mask:0xf
	s_not_b64 vcc, s[6:7]
	v_cndmask_b32_dpp v48, v234, v238, vcc row_ror:8 row_mask:0xf bank_mask:0xf
	v_cndmask_b32_dpp v49, v235, v239, vcc row_ror:8 row_mask:0xf bank_mask:0xf
	v_cndmask_b32_dpp v50, v236, v240, vcc row_ror:8 row_mask:0xf bank_mask:0xf
	v_cndmask_b32_dpp v51, v237, v241, vcc row_ror:8 row_mask:0xf bank_mask:0xf
	global_store_dwordx4 v246, v[52:55], s[12:13]
	global_store_dwordx4 v247, v[48:51], s[12:13]
	s_waitcnt vmcnt(4)
	v_mov_b32_e32 v6, v192
	s_add_u32 s12, s12, 0x8000
	s_addc_u32 s13, s13, 0
	v_pk_fma_f32 v[38:39], v[38:39], v[6:7], v[196:197] op_sel_hi:[1,0,1]
	v_pk_fma_f32 v[36:37], v[36:37], v[6:7], v[194:195] op_sel_hi:[1,0,1]
	v_pk_fma_f32 v[34:35], v[34:35], v[6:7], v[200:201] op_sel_hi:[1,0,1]
	v_pk_fma_f32 v[32:33], v[32:33], v[6:7], v[198:199] op_sel_hi:[1,0,1]
	v_pk_fma_f32 v[30:31], v[30:31], v[6:7], v[204:205] op_sel_hi:[1,0,1]
	v_pk_fma_f32 v[28:29], v[28:29], v[6:7], v[202:203] op_sel_hi:[1,0,1]
	v_pk_fma_f32 v[26:27], v[26:27], v[6:7], v[224:225] op_sel_hi:[1,0,1]
	v_pk_fma_f32 v[24:25], v[24:25], v[6:7], v[222:223] op_sel_hi:[1,0,1]
	v_pk_mul_f32 v[38:39], s[16:17], v[38:39]
	v_pk_mul_f32 v[36:37], s[16:17], v[36:37]
	v_pk_mul_f32 v[34:35], s[16:17], v[34:35]
	v_pk_mul_f32 v[32:33], s[16:17], v[32:33]
	v_pk_mul_f32 v[30:31], s[16:17], v[30:31]
	v_pk_mul_f32 v[28:29], s[16:17], v[28:29]
	v_pk_mul_f32 v[26:27], s[16:17], v[26:27]
	v_pk_mul_f32 v[24:25], s[16:17], v[24:25]
	v_cvt_pk_bf16_f32 v234, v36, v37
	v_cvt_pk_bf16_f32 v235, v38, v39
	v_cvt_pk_bf16_f32 v236, v32, v33
	v_cvt_pk_bf16_f32 v237, v34, v35
	v_cvt_pk_bf16_f32 v238, v28, v29
	v_cvt_pk_bf16_f32 v239, v30, v31
	v_cvt_pk_bf16_f32 v240, v24, v25
	v_cvt_pk_bf16_f32 v241, v26, v27
	s_mov_b64 vcc, s[6:7]
	v_cndmask_b32_dpp v36, v238, v234, vcc row_ror:8 row_mask:0xf bank_mask:0xf
	v_cndmask_b32_dpp v37, v239, v235, vcc row_ror:8 row_mask:0xf bank_mask:0xf
	v_cndmask_b32_dpp v38, v240, v236, vcc row_ror:8 row_mask:0xf bank_mask:0xf
	v_cndmask_b32_dpp v39, v241, v237, vcc row_ror:8 row_mask:0xf bank_mask:0xf
	s_not_b64 vcc, s[6:7]
	v_cndmask_b32_dpp v32, v234, v238, vcc row_ror:8 row_mask:0xf bank_mask:0xf
	v_cndmask_b32_dpp v33, v235, v239, vcc row_ror:8 row_mask:0xf bank_mask:0xf
	v_cndmask_b32_dpp v34, v236, v240, vcc row_ror:8 row_mask:0xf bank_mask:0xf
	v_cndmask_b32_dpp v35, v237, v241, vcc row_ror:8 row_mask:0xf bank_mask:0xf
	global_store_dwordx4 v246, v[36:39], s[12:13]
	global_store_dwordx4 v247, v[32:35], s[12:13]
	v_mov_b32_e32 v6, v193
	s_add_u32 s12, s12, 0x8000
	s_addc_u32 s13, s13, 0
	v_pk_fma_f32 v[22:23], v[22:23], v[6:7], v[196:197] op_sel_hi:[1,0,1]
	v_pk_fma_f32 v[20:21], v[20:21], v[6:7], v[194:195] op_sel_hi:[1,0,1]
	v_pk_fma_f32 v[18:19], v[18:19], v[6:7], v[200:201] op_sel_hi:[1,0,1]
	v_pk_fma_f32 v[16:17], v[16:17], v[6:7], v[198:199] op_sel_hi:[1,0,1]
	v_pk_fma_f32 v[14:15], v[14:15], v[6:7], v[204:205] op_sel_hi:[1,0,1]
	v_pk_fma_f32 v[12:13], v[12:13], v[6:7], v[202:203] op_sel_hi:[1,0,1]
	v_pk_fma_f32 v[10:11], v[10:11], v[6:7], v[224:225] op_sel_hi:[1,0,1]
	v_pk_fma_f32 v[8:9], v[8:9], v[6:7], v[222:223] op_sel_hi:[1,0,1]
	v_pk_mul_f32 v[22:23], s[16:17], v[22:23]
	v_pk_mul_f32 v[20:21], s[16:17], v[20:21]
	v_pk_mul_f32 v[18:19], s[16:17], v[18:19]
	v_pk_mul_f32 v[16:17], s[16:17], v[16:17]
	v_pk_mul_f32 v[14:15], s[16:17], v[14:15]
	v_pk_mul_f32 v[12:13], s[16:17], v[12:13]
	v_pk_mul_f32 v[10:11], s[16:17], v[10:11]
	v_pk_mul_f32 v[8:9], s[16:17], v[8:9]
	v_cvt_pk_bf16_f32 v234, v20, v21
	v_cvt_pk_bf16_f32 v235, v22, v23
	v_cvt_pk_bf16_f32 v236, v16, v17
	v_cvt_pk_bf16_f32 v237, v18, v19
	v_cvt_pk_bf16_f32 v238, v12, v13
	v_cvt_pk_bf16_f32 v239, v14, v15
	v_cvt_pk_bf16_f32 v240, v8, v9
	v_cvt_pk_bf16_f32 v241, v10, v11
	s_mov_b64 vcc, s[6:7]
	v_cndmask_b32_dpp v20, v238, v234, vcc row_ror:8 row_mask:0xf bank_mask:0xf
	v_cndmask_b32_dpp v21, v239, v235, vcc row_ror:8 row_mask:0xf bank_mask:0xf
	v_cndmask_b32_dpp v22, v240, v236, vcc row_ror:8 row_mask:0xf bank_mask:0xf
	v_cndmask_b32_dpp v23, v241, v237, vcc row_ror:8 row_mask:0xf bank_mask:0xf
	s_not_b64 vcc, s[6:7]
	v_cndmask_b32_dpp v16, v234, v238, vcc row_ror:8 row_mask:0xf bank_mask:0xf
	v_cndmask_b32_dpp v17, v235, v239, vcc row_ror:8 row_mask:0xf bank_mask:0xf
	v_cndmask_b32_dpp v18, v236, v240, vcc row_ror:8 row_mask:0xf bank_mask:0xf
	v_cndmask_b32_dpp v19, v237, v241, vcc row_ror:8 row_mask:0xf bank_mask:0xf
	global_store_dwordx4 v246, v[20:23], s[12:13]
	global_store_dwordx4 v247, v[16:19], s[12:13]
	s_mov_b32 s100, 1
	s_branch .LBB0_1422
.Lfn_kind1:
	s_and_b64 vcc, exec, s[2:3]
	s_cbranch_vccz .Lfn_plain
	s_waitcnt vmcnt(4)
	v_mov_b32_e32 v6, v186
	v_pk_fma_f32 v[136:137], v[136:137], v[6:7], v[152:153] op_sel_hi:[1,0,1]
	v_pk_fma_f32 v[134:135], v[134:135], v[6:7], v[150:151] op_sel_hi:[1,0,1]
	v_pk_fma_f32 v[132:133], v[132:133], v[6:7], v[148:149] op_sel_hi:[1,0,1]
	v_pk_fma_f32 v[130:131], v[130:131], v[6:7], v[146:147] op_sel_hi:[1,0,1]
	v_pk_fma_f32 v[128:129], v[128:129], v[6:7], v[144:145] op_sel_hi:[1,0,1]
	v_pk_fma_f32 v[126:127], v[126:127], v[6:7], v[142:143] op_sel_hi:[1,0,1]
	v_pk_fma_f32 v[124:125], v[124:125], v[6:7], v[140:141] op_sel_hi:[1,0,1]
	v_pk_fma_f32 v[122:123], v[122:123], v[6:7], v[138:139] op_sel_hi:[1,0,1]
	v_mul_f32_e32 v0, 0xbfb8aa3b, v134
	v_mul_f32_e32 v1, 0xbfb8aa3b, v135
	v_mul_f32_e32 v2, 0xbfb8aa3b, v136
	v_mul_f32_e32 v3, 0xbfb8aa3b, v137
	v_mul_f32_e32 v242, 0xbfb8aa3b, v130
	v_mul_f32_e32 v243, 0xbfb8aa3b, v131
	v_mul_f32_e32 v244, 0xbfb8aa3b, v132
	v_mul_f32_e32 v245, 0xbfb8aa3b, v133
	v_exp_f32_e32 v0, v0
	v_exp_f32_e32 v1, v1
	v_exp_f32_e32 v2, v2
	v_exp_f32_e32 v3, v3
	v_exp_f32_e32 v242, v242
	v_exp_f32_e32 v243, v243
	v_exp_f32_e32 v244, v244
	v_exp_f32_e32 v245, v245
	v_add_f32_e32 v0, 1.0, v0
	v_add_f32_e32 v1, 1.0, v1
	v_add_f32_e32 v2, 1.0, v2
	v_add_f32_e32 v3, 1.0, v3
	v_add_f32_e32 v242, 1.0, v242
	v_add_f32_e32 v243, 1.0, v243
	v_add_f32_e32 v244, 1.0, v244
	v_add_f32_e32 v245, 1.0, v245
	v_rcp_f32_e32 v0, v0
	v_rcp_f32_e32 v1, v1
	v_rcp_f32_e32 v2, v2
	v_rcp_f32_e32 v3, v3
	v_rcp_f32_e32 v242, v242
	v_rcp_f32_e32 v243, v243
	v_rcp_f32_e32 v244, v244
	v_rcp_f32_e32 v245, v245
	v_pk_mul_f32 v[134:135], v[134:135], v[0:1]
	v_pk_mul_f32 v[136:137], v[136:137], v[2:3]
	v_pk_mul_f32 v[130:131], v[130:131], v[242:243]
	v_pk_mul_f32 v[132:133], v[132:133], v[244:245]
	v_mul_f32_e32 v0, 0xbfb8aa3b, v126
	v_mul_f32_e32 v1, 0xbfb8aa3b, v127
	v_mul_f32_e32 v2, 0xbfb8aa3b, v128
	v_mul_f32_e32 v3, 0xbfb8aa3b, v129
	v_mul_f32_e32 v242, 0xbfb8aa3b, v122
	v_mul_f32_e32 v243, 0xbfb8aa3b, v123
	v_mul_f32_e32 v244, 0xbfb8aa3b, v124
	v_mul_f32_e32 v245, 0xbfb8aa3b, v125
	v_exp_f32_e32 v0, v0
	v_exp_f32_e32 v1, v1
	v_exp_f32_e32 v2, v2
	v_exp_f32_e32 v3, v3
	v_exp_f32_e32 v242, v242
	v_exp_f32_e32 v243, v243
	v_exp_f32_e32 v244, v244
	v_exp_f32_e32 v245, v245
	v_add_f32_e32 v0, 1.0, v0
	v_add_f32_e32 v1, 1.0, v1
	v_add_f32_e32 v2, 1.0, v2
	v_add_f32_e32 v3, 1.0, v3
	v_add_f32_e32 v242, 1.0, v242
	v_add_f32_e32 v243, 1.0, v243
	v_add_f32_e32 v244, 1.0, v244
	v_add_f32_e32 v245, 1.0, v245
	v_rcp_f32_e32 v0, v0
	v_rcp_f32_e32 v1, v1
	v_rcp_f32_e32 v2, v2
	v_rcp_f32_e32 v3, v3
	v_rcp_f32_e32 v242, v242
	v_rcp_f32_e32 v243, v243
	v_rcp_f32_e32 v244, v244
	v_rcp_f32_e32 v245, v245
	v_pk_mul_f32 v[126:127], v[126:127], v[0:1]
	v_pk_mul_f32 v[128:129], v[128:129], v[2:3]
	v_pk_mul_f32 v[122:123], v[122:123], v[242:243]
	v_pk_mul_f32 v[124:125], v[124:125], v[244:245]
	v_cvt_pk_bf16_f32 v234, v134, v135
	v_cvt_pk_bf16_f32 v235, v136, v137
	v_cvt_pk_bf16_f32 v236, v130, v131
	v_cvt_pk_bf16_f32 v237, v132, v133
	v_cvt_pk_bf16_f32 v238, v126, v127
	v_cvt_pk_bf16_f32 v239, v128, v129
	v_cvt_pk_bf16_f32 v240, v122, v123
	v_cvt_pk_bf16_f32 v241, v124, v125
	s_mov_b64 vcc, s[6:7]
	v_cndmask_b32_dpp v134, v238, v234, vcc row_ror:8 row_mask:0xf bank_mask:0xf
	v_cndmask_b32_dpp v135, v239, v235, vcc row_ror:8 row_mask:0xf bank_mask:0xf
	v_cndmask_b32_dpp v136, v240, v236, vcc row_ror:8 row_mask:0xf bank_mask:0xf
	v_cndmask_b32_dpp v137, v241, v237, vcc row_ror:8 row_mask:0xf bank_mask:0xf
	s_not_b64 vcc, s[6:7]
	v_cndmask_b32_dpp v130, v234, v238, vcc row_ror:8 row_mask:0xf bank_mask:0xf
	v_cndmask_b32_dpp v131, v235, v239, vcc row_ror:8 row_mask:0xf bank_mask:0xf
	v_cndmask_b32_dpp v132, v236, v240, vcc row_ror:8 row_mask:0xf bank_mask:0xf
	v_cndmask_b32_dpp v133, v237, v241, vcc row_ror:8 row_mask:0xf bank_mask:0xf
	global_store_dwordx4 v246, v[134:137], s[12:13]
	global_store_dwordx4 v247, v[130:133], s[12:13]
	v_mov_b32_e32 v6, v187
	s_add_u32 s12, s12, 0x8000
	s_addc_u32 s13, s13, 0
	v_pk_fma_f32 v[120:121], v[120:121], v[6:7], v[152:153] op_sel_hi:[1,0,1]
	v_pk_fma_f32 v[118:119], v[118:119], v[6:7], v[150:151] op_sel_hi:[1,0,1]
	v_pk_fma_f32 v[116:117], v[116:117], v[6:7], v[148:149] op_sel_hi:[1,0,1]
	v_pk_fma_f32 v[114:115], v[114:115], v[6:7], v[146:147] op_sel_hi:[1,0,1]
	v_pk_fma_f32 v[112:113], v[112:113], v[6:7], v[144:145] op_sel_hi:[1,0,1]
	v_pk_fma_f32 v[110:111], v[110:111], v[6:7], v[142:143] op_sel_hi:[1,0,1]
	v_pk_fma_f32 v[108:109], v[108:109], v[6:7], v[140:141] op_sel_hi:[1,0,1]
	v_pk_fma_f32 v[106:107], v[106:107], v[6:7], v[138:139] op_sel_hi:[1,0,1]
	v_mul_f32_e32 v0, 0xbfb8aa3b, v118
	v_mul_f32_e32 v1, 0xbfb8aa3b, v119
	v_mul_f32_e32 v2, 0xbfb8aa3b, v120
	v_mul_f32_e32 v3, 0xbfb8aa3b, v121
	v_mul_f32_e32 v242, 0xbfb8aa3b, v114
	v_mul_f32_e32 v243, 0xbfb8aa3b, v115
	v_mul_f32_e32 v244, 0xbfb8aa3b, v116
	v_mul_f32_e32 v245, 0xbfb8aa3b, v117
	v_exp_f32_e32 v0, v0
	v_exp_f32_e32 v1, v1
	v_exp_f32_e32 v2, v2
	v_exp_f32_e32 v3, v3
	v_exp_f32_e32 v242, v242
	v_exp_f32_e32 v243, v243
	v_exp_f32_e32 v244, v244
	v_exp_f32_e32 v245, v245
	v_add_f32_e32 v0, 1.0, v0
	v_add_f32_e32 v1, 1.0, v1
	v_add_f32_e32 v2, 1.0, v2
	v_add_f32_e32 v3, 1.0, v3
	v_add_f32_e32 v242, 1.0, v242
	v_add_f32_e32 v243, 1.0, v243
	v_add_f32_e32 v244, 1.0, v244
	v_add_f32_e32 v245, 1.0, v245
	v_rcp_f32_e32 v0, v0
	v_rcp_f32_e32 v1, v1
	v_rcp_f32_e32 v2, v2
	v_rcp_f32_e32 v3, v3
	v_rcp_f32_e32 v242, v242
	v_rcp_f32_e32 v243, v243
	v_rcp_f32_e32 v244, v244
	v_rcp_f32_e32 v245, v245
	v_pk_mul_f32 v[118:119], v[118:119], v[0:1]
	v_pk_mul_f32 v[120:121], v[120:121], v[2:3]
	v_pk_mul_f32 v[114:115], v[114:115], v[242:243]
	v_pk_mul_f32 v[116:117], v[116:117], v[244:245]
	v_mul_f32_e32 v0, 0xbfb8aa3b, v110
	v_mul_f32_e32 v1, 0xbfb8aa3b, v111
	v_mul_f32_e32 v2, 0xbfb8aa3b, v112
	v_mul_f32_e32 v3, 0xbfb8aa3b, v113
	v_mul_f32_e32 v242, 0xbfb8aa3b, v106
	v_mul_f32_e32 v243, 0xbfb8aa3b, v107
	v_mul_f32_e32 v244, 0xbfb8aa3b, v108
	v_mul_f32_e32 v245, 0xbfb8aa3b, v109
	v_exp_f32_e32 v0, v0
	v_exp_f32_e32 v1, v1
	v_exp_f32_e32 v2, v2
	v_exp_f32_e32 v3, v3
	v_exp_f32_e32 v242, v242
	v_exp_f32_e32 v243, v243
	v_exp_f32_e32 v244, v244
	v_exp_f32_e32 v245, v245
	v_add_f32_e32 v0, 1.0, v0
	v_add_f32_e32 v1, 1.0, v1
	v_add_f32_e32 v2, 1.0, v2
	v_add_f32_e32 v3, 1.0, v3
	v_add_f32_e32 v242, 1.0, v242
	v_add_f32_e32 v243, 1.0, v243
	v_add_f32_e32 v244, 1.0, v244
	v_add_f32_e32 v245, 1.0, v245
	v_rcp_f32_e32 v0, v0
	v_rcp_f32_e32 v1, v1
	v_rcp_f32_e32 v2, v2
	v_rcp_f32_e32 v3, v3
	v_rcp_f32_e32 v242, v242
	v_rcp_f32_e32 v243, v243
	v_rcp_f32_e32 v244, v244
	v_rcp_f32_e32 v245, v245
	v_pk_mul_f32 v[110:111], v[110:111], v[0:1]
	v_pk_mul_f32 v[112:113], v[112:113], v[2:3]
	v_pk_mul_f32 v[106:107], v[106:107], v[242:243]
	v_pk_mul_f32 v[108:109], v[108:109], v[244:245]
	v_cvt_pk_bf16_f32 v234, v118, v119
	v_cvt_pk_bf16_f32 v235, v120, v121
	v_cvt_pk_bf16_f32 v236, v114, v115
	v_cvt_pk_bf16_f32 v237, v116, v117
	v_cvt_pk_bf16_f32 v238, v110, v111
	v_cvt_pk_bf16_f32 v239, v112, v113
	v_cvt_pk_bf16_f32 v240, v106, v107
	v_cvt_pk_bf16_f32 v241, v108, v109
	s_mov_b64 vcc, s[6:7]
	v_cndmask_b32_dpp v118, v238, v234, vcc row_ror:8 row_mask:0xf bank_mask:0xf
	v_cndmask_b32_dpp v119, v239, v235, vcc row_ror:8 row_mask:0xf bank_mask:0xf
	v_cndmask_b32_dpp v120, v240, v236, vcc row_ror:8 row_mask:0xf bank_mask:0xf
	v_cndmask_b32_dpp v121, v241, v237, vcc row_ror:8 row_mask:0xf bank_mask:0xf
	s_not_b64 vcc, s[6:7]
	v_cndmask_b32_dpp v114, v234, v238, vcc row_ror:8 row_mask:0xf bank_mask:0xf
	v_cndmask_b32_dpp v115, v235, v239, vcc row_ror:8 row_mask:0xf bank_mask:0xf
	v_cndmask_b32_dpp v116, v236, v240, vcc row_ror:8 row_mask:0xf bank_mask:0xf
	v_cndmask_b32_dpp v117, v237, v241, vcc row_ror:8 row_mask:0xf bank_mask:0xf
	global_store_dwordx4 v246, v[118:121], s[12:13]
	global_store_dwordx4 v247, v[114:117], s[12:13]
	s_add_u32 s10, s10, 0x9000
	s_addc_u32 s11, s11, 0
	global_load_dwordx4 v[150:153], v226, s[10:11]
	global_load_dwordx4 v[146:149], v226, s[10:11] offset:16
	global_load_dwordx4 v[142:145], v226, s[10:11] offset:128
	global_load_dwordx4 v[138:141], v226, s[10:11] offset:144
	s_waitcnt vmcnt(8)
	v_mov_b32_e32 v6, v188
	s_add_u32 s12, s12, 0x8000
	s_addc_u32 s13, s13, 0
	v_pk_fma_f32 v[104:105], v[104:105], v[6:7], v[196:197] op_sel_hi:[1,0,1]
	v_pk_fma_f32 v[102:103], v[102:103], v[6:7], v[194:195] op_sel_hi:[1,0,1]
	v_pk_fma_f32 v[100:101], v[100:101], v[6:7], v[200:201] op_sel_hi:[1,0,1]
	v_pk_fma_f32 v[98:99], v[98:99], v[6:7], v[198:199] op_sel_hi:[1,0,1]
	v_pk_fma_f32 v[94:95], v[94:95], v[6:7], v[204:205] op_sel_hi:[1,0,1]
	v_pk_fma_f32 v[92:93], v[92:93], v[6:7], v[202:203] op_sel_hi:[1,0,1]
	v_pk_fma_f32 v[90:91], v[90:91], v[6:7], v[224:225] op_sel_hi:[1,0,1]
	v_pk_fma_f32 v[88:89], v[88:89], v[6:7], v[222:223] op_sel_hi:[1,0,1]
	v_mul_f32_e32 v0, 0xbfb8aa3b, v102
	v_mul_f32_e32 v1, 0xbfb8aa3b, v103
	v_mul_f32_e32 v2, 0xbfb8aa3b, v104
	v_mul_f32_e32 v3, 0xbfb8aa3b, v105
	v_mul_f32_e32 v242, 0xbfb8aa3b, v98
	v_mul_f32_e32 v243, 0xbfb8aa3b, v99
	v_mul_f32_e32 v244, 0xbfb8aa3b, v100
	v_mul_f32_e32 v245, 0xbfb8aa3b, v101
	v_exp_f32_e32 v0, v0
	v_exp_f32_e32 v1, v1
	v_exp_f32_e32 v2, v2
	v_exp_f32_e32 v3, v3
	v_exp_f32_e32 v242, v242
	v_exp_f32_e32 v243, v243
	v_exp_f32_e32 v244, v244
	v_exp_f32_e32 v245, v245
	v_add_f32_e32 v0, 1.0, v0
	v_add_f32_e32 v1, 1.0, v1
	v_add_f32_e32 v2, 1.0, v2
	v_add_f32_e32 v3, 1.0, v3
	v_add_f32_e32 v242, 1.0, v242
	v_add_f32_e32 v243, 1.0, v243
	v_add_f32_e32 v244, 1.0, v244
	v_add_f32_e32 v245, 1.0, v245
	v_rcp_f32_e32 v0, v0
	v_rcp_f32_e32 v1, v1
	v_rcp_f32_e32 v2, v2
	v_rcp_f32_e32 v3, v3
	v_rcp_f32_e32 v242, v242
	v_rcp_f32_e32 v243, v243
	v_rcp_f32_e32 v244, v244
	v_rcp_f32_e32 v245, v245
	v_pk_mul_f32 v[102:103], v[102:103], v[0:1]
	v_pk_mul_f32 v[104:105], v[104:105], v[2:3]
	v_pk_mul_f32 v[98:99], v[98:99], v[242:243]
	v_pk_mul_f32 v[100:101], v[100:101], v[244:245]
	v_mul_f32_e32 v0, 0xbfb8aa3b, v92
	v_mul_f32_e32 v1, 0xbfb8aa3b, v93
	v_mul_f32_e32 v2, 0xbfb8aa3b, v94
	v_mul_f32_e32 v3, 0xbfb8aa3b, v95
	v_mul_f32_e32 v242, 0xbfb8aa3b, v88
	v_mul_f32_e32 v243, 0xbfb8aa3b, v89
	v_mul_f32_e32 v244, 0xbfb8aa3b, v90
	v_mul_f32_e32 v245, 0xbfb8aa3b, v91
	v_exp_f32_e32 v0, v0
	v_exp_f32_e32 v1, v1
	v_exp_f32_e32 v2, v2
	v_exp_f32_e32 v3, v3
	v_exp_f32_e32 v242, v242
	v_exp_f32_e32 v243, v243
	v_exp_f32_e32 v244, v244
	v_exp_f32_e32 v245, v245
	v_add_f32_e32 v0, 1.0, v0
	v_add_f32_e32 v1, 1.0, v1
	v_add_f32_e32 v2, 1.0, v2
	v_add_f32_e32 v3, 1.0, v3
	v_add_f32_e32 v242, 1.0, v242
	v_add_f32_e32 v243, 1.0, v243
	v_add_f32_e32 v244, 1.0, v244
	v_add_f32_e32 v245, 1.0, v245
	v_rcp_f32_e32 v0, v0
	v_rcp_f32_e32 v1, v1
	v_rcp_f32_e32 v2, v2
	v_rcp_f32_e32 v3, v3
	v_rcp_f32_e32 v242, v242
	v_rcp_f32_e32 v243, v243
	v_rcp_f32_e32 v244, v244
	v_rcp_f32_e32 v245, v245
	v_pk_mul_f32 v[92:93], v[92:93], v[0:1]
	v_pk_mul_f32 v[94:95], v[94:95], v[2:3]
	v_pk_mul_f32 v[88:89], v[88:89], v[242:243]
	v_pk_mul_f32 v[90:91], v[90:91], v[244:245]
	v_cvt_pk_bf16_f32 v234, v102, v103
	v_cvt_pk_bf16_f32 v235, v104, v105
	v_cvt_pk_bf16_f32 v236, v98, v99
	v_cvt_pk_bf16_f32 v237, v100, v101
	v_cvt_pk_bf16_f32 v238, v92, v93
	v_cvt_pk_bf16_f32 v239, v94, v95
	v_cvt_pk_bf16_f32 v240, v88, v89
	v_cvt_pk_bf16_f32 v241, v90, v91
	s_mov_b64 vcc, s[6:7]
	v_cndmask_b32_dpp v102, v238, v234, vcc row_ror:8 row_mask:0xf bank_mask:0xf
	v_cndmask_b32_dpp v103, v239, v235, vcc row_ror:8 row_mask:0xf bank_mask:0xf
	v_cndmask_b32_dpp v104, v240, v236, vcc row_ror:8 row_mask:0xf bank_mask:0xf
	v_cndmask_b32_dpp v105, v241, v237, vcc row_ror:8 row_mask:0xf bank_mask:0xf
	s_not_b64 vcc, s[6:7]
	v_cndmask_b32_dpp v98, v234, v238, vcc row_ror:8 row_mask:0xf bank_mask:0xf
	v_cndmask_b32_dpp v99, v235, v239, vcc row_ror:8 row_mask:0xf bank_mask:0xf
	v_cndmask_b32_dpp v100, v236, v240, vcc row_ror:8 row_mask:0xf bank_mask:0xf
	v_cndmask_b32_dpp v101, v237, v241, vcc row_ror:8 row_mask:0xf bank_mask:0xf
	global_store_dwordx4 v246, v[102:105], s[12:13]
	global_store_dwordx4 v247, v[98:101], s[12:13]
	v_mov_b32_e32 v6, v189
	s_add_u32 s12, s12, 0x8000
	s_addc_u32 s13, s13, 0
	v_pk_fma_f32 v[86:87], v[86:87], v[6:7], v[196:197] op_sel_hi:[1,0,1]
	v_pk_fma_f32 v[84:85], v[84:85], v[6:7], v[194:195] op_sel_hi:[1,0,1]
	v_pk_fma_f32 v[82:83], v[82:83], v[6:7], v[200:201] op_sel_hi:[1,0,1]
	v_pk_fma_f32 v[80:81], v[80:81], v[6:7], v[198:199] op_sel_hi:[1,0,1]
	v_pk_fma_f32 v[78:79], v[78:79], v[6:7], v[204:205] op_sel_hi:[1,0,1]
	v_pk_fma_f32 v[76:77], v[76:77], v[6:7], v[202:203] op_sel_hi:[1,0,1]
	v_pk_fma_f32 v[74:75], v[74:75], v[6:7], v[224:225] op_sel_hi:[1,0,1]
	v_pk_fma_f32 v[72:73], v[72:73], v[6:7], v[222:223] op_sel_hi:[1,0,1]
	v_mul_f32_e32 v0, 0xbfb8aa3b, v84
	v_mul_f32_e32 v1, 0xbfb8aa3b, v85
	v_mul_f32_e32 v2, 0xbfb8aa3b, v86
	v_mul_f32_e32 v3, 0xbfb8aa3b, v87
	v_mul_f32_e32 v242, 0xbfb8aa3b, v80
	v_mul_f32_e32 v243, 0xbfb8aa3b, v81
	v_mul_f32_e32 v244, 0xbfb8aa3b, v82
	v_mul_f32_e32 v245, 0xbfb8aa3b, v83
	v_exp_f32_e32 v0, v0
	v_exp_f32_e32 v1, v1
	v_exp_f32_e32 v2, v2
	v_exp_f32_e32 v3, v3
	v_exp_f32_e32 v242, v242
	v_exp_f32_e32 v243, v243
	v_exp_f32_e32 v244, v244
	v_exp_f32_e32 v245, v245
	v_add_f32_e32 v0, 1.0, v0
	v_add_f32_e32 v1, 1.0, v1
	v_add_f32_e32 v2, 1.0, v2
	v_add_f32_e32 v3, 1.0, v3
	v_add_f32_e32 v242, 1.0, v242
	v_add_f32_e32 v243, 1.0, v243
	v_add_f32_e32 v244, 1.0, v244
	v_add_f32_e32 v245, 1.0, v245
	v_rcp_f32_e32 v0, v0
	v_rcp_f32_e32 v1, v1
	v_rcp_f32_e32 v2, v2
	v_rcp_f32_e32 v3, v3
	v_rcp_f32_e32 v242, v242
	v_rcp_f32_e32 v243, v243
	v_rcp_f32_e32 v244, v244
	v_rcp_f32_e32 v245, v245
	v_pk_mul_f32 v[84:85], v[84:85], v[0:1]
	v_pk_mul_f32 v[86:87], v[86:87], v[2:3]
	v_pk_mul_f32 v[80:81], v[80:81], v[242:243]
	v_pk_mul_f32 v[82:83], v[82:83], v[244:245]
	v_mul_f32_e32 v0, 0xbfb8aa3b, v76
	v_mul_f32_e32 v1, 0xbfb8aa3b, v77
	v_mul_f32_e32 v2, 0xbfb8aa3b, v78
	v_mul_f32_e32 v3, 0xbfb8aa3b, v79
	v_mul_f32_e32 v242, 0xbfb8aa3b, v72
	v_mul_f32_e32 v243, 0xbfb8aa3b, v73
	v_mul_f32_e32 v244, 0xbfb8aa3b, v74
	v_mul_f32_e32 v245, 0xbfb8aa3b, v75
	v_exp_f32_e32 v0, v0
	v_exp_f32_e32 v1, v1
	v_exp_f32_e32 v2, v2
	v_exp_f32_e32 v3, v3
	v_exp_f32_e32 v242, v242
	v_exp_f32_e32 v243, v243
	v_exp_f32_e32 v244, v244
	v_exp_f32_e32 v245, v245
	v_add_f32_e32 v0, 1.0, v0
	v_add_f32_e32 v1, 1.0, v1
	v_add_f32_e32 v2, 1.0, v2
	v_add_f32_e32 v3, 1.0, v3
	v_add_f32_e32 v242, 1.0, v242
	v_add_f32_e32 v243, 1.0, v243
	v_add_f32_e32 v244, 1.0, v244
	v_add_f32_e32 v245, 1.0, v245
	v_rcp_f32_e32 v0, v0
	v_rcp_f32_e32 v1, v1
	v_rcp_f32_e32 v2, v2
	v_rcp_f32_e32 v3, v3
	v_rcp_f32_e32 v242, v242
	v_rcp_f32_e32 v243, v243
	v_rcp_f32_e32 v244, v244
	v_rcp_f32_e32 v245, v245
	v_pk_mul_f32 v[76:77], v[76:77], v[0:1]
	v_pk_mul_f32 v[78:79], v[78:79], v[2:3]
	v_pk_mul_f32 v[72:73], v[72:73], v[242:243]
	v_pk_mul_f32 v[74:75], v[74:75], v[244:245]
	v_cvt_pk_bf16_f32 v234, v84, v85
	v_cvt_pk_bf16_f32 v235, v86, v87
	v_cvt_pk_bf16_f32 v236, v80, v81
	v_cvt_pk_bf16_f32 v237, v82, v83
	v_cvt_pk_bf16_f32 v238, v76, v77
	v_cvt_pk_bf16_f32 v239, v78, v79
	v_cvt_pk_bf16_f32 v240, v72, v73
	v_cvt_pk_bf16_f32 v241, v74, v75
	s_mov_b64 vcc, s[6:7]
	v_cndmask_b32_dpp v84, v238, v234, vcc row_ror:8 row_mask:0xf bank_mask:0xf
	v_cndmask_b32_dpp v85, v239, v235, vcc row_ror:8 row_mask:0xf bank_mask:0xf
	v_cndmask_b32_dpp v86, v240, v236, vcc row_ror:8 row_mask:0xf bank_mask:0xf
	v_cndmask_b32_dpp v87, v241, v237, vcc row_ror:8 row_mask:0xf bank_mask:0xf
	s_not_b64 vcc, s[6:7]
	v_cndmask_b32_dpp v80, v234, v238, vcc row_ror:8 row_mask:0xf bank_mask:0xf
	v_cndmask_b32_dpp v81, v235, v239, vcc row_ror:8 row_mask:0xf bank_mask:0xf
	v_cndmask_b32_dpp v82, v236, v240, vcc row_ror:8 row_mask:0xf bank_mask:0xf
	v_cndmask_b32_dpp v83, v237, v241, vcc row_ror:8 row_mask:0xf bank_mask:0xf
	global_store_dwordx4 v246, v[84:87], s[12:13]
	global_store_dwordx4 v247, v[80:83], s[12:13]
	s_add_u32 s10, s10, 0x3000
	s_addc_u32 s11, s11, 0
	global_load_dwordx4 v[194:197], v226, s[10:11]
	global_load_dwordx4 v[198:201], v226, s[10:11] offset:16
	global_load_dwordx4 v[202:205], v226, s[10:11] offset:128
	global_load_dwordx4 v[222:225], v226, s[10:11] offset:144
	s_waitcnt vmcnt(8)
	v_mov_b32_e32 v6, v190
	s_add_u32 s12, s12, 0x28000
	s_addc_u32 s13, s13, 0
	v_pk_fma_f32 v[70:71], v[70:71], v[6:7], v[152:153] op_sel_hi:[1,0,1]
	v_pk_fma_f32 v[68:69], v[68:69], v[6:7], v[150:151] op_sel_hi:[1,0,1]
	v_pk_fma_f32 v[66:67], v[66:67], v[6:7], v[148:149] op_sel_hi:[1,0,1]
	v_pk_fma_f32 v[64:65], v[64:65], v[6:7], v[146:147] op_sel_hi:[1,0,1]
	v_pk_fma_f32 v[62:63], v[62:63], v[6:7], v[144:145] op_sel_hi:[1,0,1]
	v_pk_fma_f32 v[60:61], v[60:61], v[6:7], v[142:143] op_sel_hi:[1,0,1]
	v_pk_fma_f32 v[58:59], v[58:59], v[6:7], v[140:141] op_sel_hi:[1,0,1]
	v_pk_fma_f32 v[56:57], v[56:57], v[6:7], v[138:139] op_sel_hi:[1,0,1]
	v_mul_f32_e32 v0, 0xbfb8aa3b, v68
	v_mul_f32_e32 v1, 0xbfb8aa3b, v69
	v_mul_f32_e32 v2, 0xbfb8aa3b, v70
	v_mul_f32_e32 v3, 0xbfb8aa3b, v71
	v_mul_f32_e32 v242, 0xbfb8aa3b, v64
	v_mul_f32_e32 v243, 0xbfb8aa3b, v65
	v_mul_f32_e32 v244, 0xbfb8aa3b, v66
	v_mul_f32_e32 v245, 0xbfb8aa3b, v67
	v_exp_f32_e32 v0, v0
	v_exp_f32_e32 v1, v1
	v_exp_f32_e32 v2, v2
	v_exp_f32_e32 v3, v3
	v_exp_f32_e32 v242, v242
	v_exp_f32_e32 v243, v243
	v_exp_f32_e32 v244, v244
	v_exp_f32_e32 v245, v245
	v_add_f32_e32 v0, 1.0, v0
	v_add_f32_e32 v1, 1.0, v1
	v_add_f32_e32 v2, 1.0, v2
	v_add_f32_e32 v3, 1.0, v3
	v_add_f32_e32 v242, 1.0, v242
	v_add_f32_e32 v243, 1.0, v243
	v_add_f32_e32 v244, 1.0, v244
	v_add_f32_e32 v245, 1.0, v245
	v_rcp_f32_e32 v0, v0
	v_rcp_f32_e32 v1, v1
	v_rcp_f32_e32 v2, v2
	v_rcp_f32_e32 v3, v3
	v_rcp_f32_e32 v242, v242
	v_rcp_f32_e32 v243, v243
	v_rcp_f32_e32 v244, v244
	v_rcp_f32_e32 v245, v245
	v_pk_mul_f32 v[68:69], v[68:69], v[0:1]
	v_pk_mul_f32 v[70:71], v[70:71], v[2:3]
	v_pk_mul_f32 v[64:65], v[64:65], v[242:243]
	v_pk_mul_f32 v[66:67], v[66:67], v[244:245]
	v_mul_f32_e32 v0, 0xbfb8aa3b, v60
	v_mul_f32_e32 v1, 0xbfb8aa3b, v61
	v_mul_f32_e32 v2, 0xbfb8aa3b, v62
	v_mul_f32_e32 v3, 0xbfb8aa3b, v63
	v_mul_f32_e32 v242, 0xbfb8aa3b, v56
	v_mul_f32_e32 v243, 0xbfb8aa3b, v57
	v_mul_f32_e32 v244, 0xbfb8aa3b, v58
	v_mul_f32_e32 v245, 0xbfb8aa3b, v59
	v_exp_f32_e32 v0, v0
	v_exp_f32_e32 v1, v1
	v_exp_f32_e32 v2, v2
	v_exp_f32_e32 v3, v3
	v_exp_f32_e32 v242, v242
	v_exp_f32_e32 v243, v243
	v_exp_f32_e32 v244, v244
	v_exp_f32_e32 v245, v245
	v_add_f32_e32 v0, 1.0, v0
	v_add_f32_e32 v1, 1.0, v1
	v_add_f32_e32 v2, 1.0, v2
	v_add_f32_e32 v3, 1.0, v3
	v_add_f32_e32 v242, 1.0, v242
	v_add_f32_e32 v243, 1.0, v243
	v_add_f32_e32 v244, 1.0, v244
	v_add_f32_e32 v245, 1.0, v245
	v_rcp_f32_e32 v0, v0
	v_rcp_f32_e32 v1, v1
	v_rcp_f32_e32 v2, v2
	v_rcp_f32_e32 v3, v3
	v_rcp_f32_e32 v242, v242
	v_rcp_f32_e32 v243, v243
	v_rcp_f32_e32 v244, v244
	v_rcp_f32_e32 v245, v245
	v_pk_mul_f32 v[60:61], v[60:61], v[0:1]
	v_pk_mul_f32 v[62:63], v[62:63], v[2:3]
	v_pk_mul_f32 v[56:57], v[56:57], v[242:243]
	v_pk_mul_f32 v[58:59], v[58:59], v[244:245]
	v_cvt_pk_bf16_f32 v234, v68, v69
	v_cvt_pk_bf16_f32 v235, v70, v71
	v_cvt_pk_bf16_f32 v236, v64, v65
	v_cvt_pk_bf16_f32 v237, v66, v67
	v_cvt_pk_bf16_f32 v238, v60, v61
	v_cvt_pk_bf16_f32 v239, v62, v63
	v_cvt_pk_bf16_f32 v240, v56, v57
	v_cvt_pk_bf16_f32 v241, v58, v59
	s_mov_b64 vcc, s[6:7]
	v_cndmask_b32_dpp v68, v238, v234, vcc row_ror:8 row_mask:0xf bank_mask:0xf
	v_cndmask_b32_dpp v69, v239, v235, vcc row_ror:8 row_mask:0xf bank_mask:0xf
	v_cndmask_b32_dpp v70, v240, v236, vcc row_ror:8 row_mask:0xf bank_mask:0xf
	v_cndmask_b32_dpp v71, v241, v237, vcc row_ror:8 row_mask:0xf bank_mask:0xf
	s_not_b64 vcc, s[6:7]
	v_cndmask_b32_dpp v64, v234, v238, vcc row_ror:8 row_mask:0xf bank_mask:0xf
	v_cndmask_b32_dpp v65, v235, v239, vcc row_ror:8 row_mask:0xf bank_mask:0xf
	v_cndmask_b32_dpp v66, v236, v240, vcc row_ror:8 row_mask:0xf bank_mask:0xf
	v_cndmask_b32_dpp v67, v237, v241, vcc row_ror:8 row_mask:0xf bank_mask:0xf
	global_store_dwordx4 v246, v[68:71], s[12:13]
	global_store_dwordx4 v247, v[64:67], s[12:13]
	v_mov_b32_e32 v6, v191
	s_add_u32 s12, s12, 0x8000
	s_addc_u32 s13, s13, 0
	v_pk_fma_f32 v[54:55], v[54:55], v[6:7], v[152:153] op_sel_hi:[1,0,1]
	v_pk_fma_f32 v[52:53], v[52:53], v[6:7], v[150:151] op_sel_hi:[1,0,1]
	v_pk_fma_f32 v[50:51], v[50:51], v[6:7], v[148:149] op_sel_hi:[1,0,1]
	v_pk_fma_f32 v[48:49], v[48:49], v[6:7], v[146:147] op_sel_hi:[1,0,1]
	v_pk_fma_f32 v[46:47], v[46:47], v[6:7], v[144:145] op_sel_hi:[1,0,1]
	v_pk_fma_f32 v[44:45], v[44:45], v[6:7], v[142:143] op_sel_hi:[1,0,1]
	v_pk_fma_f32 v[42:43], v[42:43], v[6:7], v[140:141] op_sel_hi:[1,0,1]
	v_pk_fma_f32 v[40:41], v[40:41], v[6:7], v[138:139] op_sel_hi:[1,0,1]
	v_mul_f32_e32 v0, 0xbfb8aa3b, v52
	v_mul_f32_e32 v1, 0xbfb8aa3b, v53
	v_mul_f32_e32 v2, 0xbfb8aa3b, v54
	v_mul_f32_e32 v3, 0xbfb8aa3b, v55
	v_mul_f32_e32 v242, 0xbfb8aa3b, v48
	v_mul_f32_e32 v243, 0xbfb8aa3b, v49
	v_mul_f32_e32 v244, 0xbfb8aa3b, v50
	v_mul_f32_e32 v245, 0xbfb8aa3b, v51
	v_exp_f32_e32 v0, v0
	v_exp_f32_e32 v1, v1
	v_exp_f32_e32 v2, v2
	v_exp_f32_e32 v3, v3
	v_exp_f32_e32 v242, v242
	v_exp_f32_e32 v243, v243
	v_exp_f32_e32 v244, v244
	v_exp_f32_e32 v245, v245
	v_add_f32_e32 v0, 1.0, v0
	v_add_f32_e32 v1, 1.0, v1
	v_add_f32_e32 v2, 1.0, v2
	v_add_f32_e32 v3, 1.0, v3
	v_add_f32_e32 v242, 1.0, v242
	v_add_f32_e32 v243, 1.0, v243
	v_add_f32_e32 v244, 1.0, v244
	v_add_f32_e32 v245, 1.0, v245
	v_rcp_f32_e32 v0, v0
	v_rcp_f32_e32 v1, v1
	v_rcp_f32_e32 v2, v2
	v_rcp_f32_e32 v3, v3
	v_rcp_f32_e32 v242, v242
	v_rcp_f32_e32 v243, v243
	v_rcp_f32_e32 v244, v244
	v_rcp_f32_e32 v245, v245
	v_pk_mul_f32 v[52:53], v[52:53], v[0:1]
	v_pk_mul_f32 v[54:55], v[54:55], v[2:3]
	v_pk_mul_f32 v[48:49], v[48:49], v[242:243]
	v_pk_mul_f32 v[50:51], v[50:51], v[244:245]
	v_mul_f32_e32 v0, 0xbfb8aa3b, v44
	v_mul_f32_e32 v1, 0xbfb8aa3b, v45
	v_mul_f32_e32 v2, 0xbfb8aa3b, v46
	v_mul_f32_e32 v3, 0xbfb8aa3b, v47
	v_mul_f32_e32 v242, 0xbfb8aa3b, v40
	v_mul_f32_e32 v243, 0xbfb8aa3b, v41
	v_mul_f32_e32 v244, 0xbfb8aa3b, v42
	v_mul_f32_e32 v245, 0xbfb8aa3b, v43
	v_exp_f32_e32 v0, v0
	v_exp_f32_e32 v1, v1
	v_exp_f32_e32 v2, v2
	v_exp_f32_e32 v3, v3
	v_exp_f32_e32 v242, v242
	v_exp_f32_e32 v243, v243
	v_exp_f32_e32 v244, v244
	v_exp_f32_e32 v245, v245
	v_add_f32_e32 v0, 1.0, v0
	v_add_f32_e32 v1, 1.0, v1
	v_add_f32_e32 v2, 1.0, v2
	v_add_f32_e32 v3, 1.0, v3
	v_add_f32_e32 v242, 1.0, v242
	v_add_f32_e32 v243, 1.0, v243
	v_add_f32_e32 v244, 1.0, v244
	v_add_f32_e32 v245, 1.0, v245
	v_rcp_f32_e32 v0, v0
	v_rcp_f32_e32 v1, v1
	v_rcp_f32_e32 v2, v2
	v_rcp_f32_e32 v3, v3
	v_rcp_f32_e32 v242, v242
	v_rcp_f32_e32 v243, v243
	v_rcp_f32_e32 v244, v244
	v_rcp_f32_e32 v245, v245
	v_pk_mul_f32 v[44:45], v[44:45], v[0:1]
	v_pk_mul_f32 v[46:47], v[46:47], v[2:3]
	v_pk_mul_f32 v[40:41], v[40:41], v[242:243]
	v_pk_mul_f32 v[42:43], v[42:43], v[244:245]
	v_cvt_pk_bf16_f32 v234, v52, v53
	v_cvt_pk_bf16_f32 v235, v54, v55
	v_cvt_pk_bf16_f32 v236, v48, v49
	v_cvt_pk_bf16_f32 v237, v50, v51
	v_cvt_pk_bf16_f32 v238, v44, v45
	v_cvt_pk_bf16_f32 v239, v46, v47
	v_cvt_pk_bf16_f32 v240, v40, v41
	v_cvt_pk_bf16_f32 v241, v42, v43
	s_mov_b64 vcc, s[6:7]
	v_cndmask_b32_dpp v52, v238, v234, vcc row_ror:8 row_mask:0xf bank_mask:0xf
	v_cndmask_b32_dpp v53, v239, v235, vcc row_ror:8 row_mask:0xf bank_mask:0xf
	v_cndmask_b32_dpp v54, v240, v236, vcc row_ror:8 row_mask:0xf bank_mask:0xf
	v_cndmask_b32_dpp v55, v241, v237, vcc row_ror:8 row_mask:0xf bank_mask:0xf
	s_not_b64 vcc, s[6:7]
	v_cndmask_b32_dpp v48, v234, v238, vcc row_ror:8 row_mask:0xf bank_mask:0xf
	v_cndmask_b32_dpp v49, v235, v239, vcc row_ror:8 row_mask:0xf bank_mask:0xf
	v_cndmask_b32_dpp v50, v236, v240, vcc row_ror:8 row_mask:0xf bank_mask:0xf
	v_cndmask_b32_dpp v51, v237, v241, vcc row_ror:8 row_mask:0xf bank_mask:0xf
	global_store_dwordx4 v246, v[52:55], s[12:13]
	global_store_dwordx4 v247, v[48:51], s[12:13]
	s_waitcnt vmcnt(4)
	v_mov_b32_e32 v6, v192
	s_add_u32 s12, s12, 0x8000
	s_addc_u32 s13, s13, 0
	v_pk_fma_f32 v[38:39], v[38:39], v[6:7], v[196:197] op_sel_hi:[1,0,1]
	v_pk_fma_f32 v[36:37], v[36:37], v[6:7], v[194:195] op_sel_hi:[1,0,1]
	v_pk_fma_f32 v[34:35], v[34:35], v[6:7], v[200:201] op_sel_hi:[1,0,1]
	v_pk_fma_f32 v[32:33], v[32:33], v[6:7], v[198:199] op_sel_hi:[1,0,1]
	v_pk_fma_f32 v[30:31], v[30:31], v[6:7], v[204:205] op_sel_hi:[1,0,1]
	v_pk_fma_f32 v[28:29], v[28:29], v[6:7], v[202:203] op_sel_hi:[1,0,1]
	v_pk_fma_f32 v[26:27], v[26:27], v[6:7], v[224:225] op_sel_hi:[1,0,1]
	v_pk_fma_f32 v[24:25], v[24:25], v[6:7], v[222:223] op_sel_hi:[1,0,1]
	v_mul_f32_e32 v0, 0xbfb8aa3b, v36
	v_mul_f32_e32 v1, 0xbfb8aa3b, v37
	v_mul_f32_e32 v2, 0xbfb8aa3b, v38
	v_mul_f32_e32 v3, 0xbfb8aa3b, v39
	v_mul_f32_e32 v242, 0xbfb8aa3b, v32
	v_mul_f32_e32 v243, 0xbfb8aa3b, v33
	v_mul_f32_e32 v244, 0xbfb8aa3b, v34
	v_mul_f32_e32 v245, 0xbfb8aa3b, v35
	v_exp_f32_e32 v0, v0
	v_exp_f32_e32 v1, v1
	v_exp_f32_e32 v2, v2
	v_exp_f32_e32 v3, v3
	v_exp_f32_e32 v242, v242
	v_exp_f32_e32 v243, v243
	v_exp_f32_e32 v244, v244
	v_exp_f32_e32 v245, v245
	v_add_f32_e32 v0, 1.0, v0
	v_add_f32_e32 v1, 1.0, v1
	v_add_f32_e32 v2, 1.0, v2
	v_add_f32_e32 v3, 1.0, v3
	v_add_f32_e32 v242, 1.0, v242
	v_add_f32_e32 v243, 1.0, v243
	v_add_f32_e32 v244, 1.0, v244
	v_add_f32_e32 v245, 1.0, v245
	v_rcp_f32_e32 v0, v0
	v_rcp_f32_e32 v1, v1
	v_rcp_f32_e32 v2, v2
	v_rcp_f32_e32 v3, v3
	v_rcp_f32_e32 v242, v242
	v_rcp_f32_e32 v243, v243
	v_rcp_f32_e32 v244, v244
	v_rcp_f32_e32 v245, v245
	v_pk_mul_f32 v[36:37], v[36:37], v[0:1]
	v_pk_mul_f32 v[38:39], v[38:39], v[2:3]
	v_pk_mul_f32 v[32:33], v[32:33], v[242:243]
	v_pk_mul_f32 v[34:35], v[34:35], v[244:245]
	v_mul_f32_e32 v0, 0xbfb8aa3b, v28
	v_mul_f32_e32 v1, 0xbfb8aa3b, v29
	v_mul_f32_e32 v2, 0xbfb8aa3b, v30
	v_mul_f32_e32 v3, 0xbfb8aa3b, v31
	v_mul_f32_e32 v242, 0xbfb8aa3b, v24
	v_mul_f32_e32 v243, 0xbfb8aa3b, v25
	v_mul_f32_e32 v244, 0xbfb8aa3b, v26
	v_mul_f32_e32 v245, 0xbfb8aa3b, v27
	v_exp_f32_e32 v0, v0
	v_exp_f32_e32 v1, v1
	v_exp_f32_e32 v2, v2
	v_exp_f32_e32 v3, v3
	v_exp_f32_e32 v242, v242
	v_exp_f32_e32 v243, v243
	v_exp_f32_e32 v244, v244
	v_exp_f32_e32 v245, v245
	v_add_f32_e32 v0, 1.0, v0
	v_add_f32_e32 v1, 1.0, v1
	v_add_f32_e32 v2, 1.0, v2
	v_add_f32_e32 v3, 1.0, v3
	v_add_f32_e32 v242, 1.0, v242
	v_add_f32_e32 v243, 1.0, v243
	v_add_f32_e32 v244, 1.0, v244
	v_add_f32_e32 v245, 1.0, v245
	v_rcp_f32_e32 v0, v0
	v_rcp_f32_e32 v1, v1
	v_rcp_f32_e32 v2, v2
	v_rcp_f32_e32 v3, v3
	v_rcp_f32_e32 v242, v242
	v_rcp_f32_e32 v243, v243
	v_rcp_f32_e32 v244, v244
	v_rcp_f32_e32 v245, v245
	v_pk_mul_f32 v[28:29], v[28:29], v[0:1]
	v_pk_mul_f32 v[30:31], v[30:31], v[2:3]
	v_pk_mul_f32 v[24:25], v[24:25], v[242:243]
	v_pk_mul_f32 v[26:27], v[26:27], v[244:245]
	v_cvt_pk_bf16_f32 v234, v36, v37
	v_cvt_pk_bf16_f32 v235, v38, v39
	v_cvt_pk_bf16_f32 v236, v32, v33
	v_cvt_pk_bf16_f32 v237, v34, v35
	v_cvt_pk_bf16_f32 v238, v28, v29
	v_cvt_pk_bf16_f32 v239, v30, v31
	v_cvt_pk_bf16_f32 v240, v24, v25
	v_cvt_pk_bf16_f32 v241, v26, v27
	s_mov_b64 vcc, s[6:7]
	v_cndmask_b32_dpp v36, v238, v234, vcc row_ror:8 row_mask:0xf bank_mask:0xf
	v_cndmask_b32_dpp v37, v239, v235, vcc row_ror:8 row_mask:0xf bank_mask:0xf
	v_cndmask_b32_dpp v38, v240, v236, vcc row_ror:8 row_mask:0xf bank_mask:0xf
	v_cndmask_b32_dpp v39, v241, v237, vcc row_ror:8 row_mask:0xf bank_mask:0xf
	s_not_b64 vcc, s[6:7]
	v_cndmask_b32_dpp v32, v234, v238, vcc row_ror:8 row_mask:0xf bank_mask:0xf
	v_cndmask_b32_dpp v33, v235, v239, vcc row_ror:8 row_mask:0xf bank_mask:0xf
	v_cndmask_b32_dpp v34, v236, v240, vcc row_ror:8 row_mask:0xf bank_mask:0xf
	v_cndmask_b32_dpp v35, v237, v241, vcc row_ror:8 row_mask:0xf bank_mask:0xf
	global_store_dwordx4 v246, v[36:39], s[12:13]
	global_store_dwordx4 v247, v[32:35], s[12:13]
	v_mov_b32_e32 v6, v193
	s_add_u32 s12, s12, 0x8000
	s_addc_u32 s13, s13, 0
	v_pk_fma_f32 v[22:23], v[22:23], v[6:7], v[196:197] op_sel_hi:[1,0,1]
	v_pk_fma_f32 v[20:21], v[20:21], v[6:7], v[194:195] op_sel_hi:[1,0,1]
	v_pk_fma_f32 v[18:19], v[18:19], v[6:7], v[200:201] op_sel_hi:[1,0,1]
	v_pk_fma_f32 v[16:17], v[16:17], v[6:7], v[198:199] op_sel_hi:[1,0,1]
	v_pk_fma_f32 v[14:15], v[14:15], v[6:7], v[204:205] op_sel_hi:[1,0,1]
	v_pk_fma_f32 v[12:13], v[12:13], v[6:7], v[202:203] op_sel_hi:[1,0,1]
	v_pk_fma_f32 v[10:11], v[10:11], v[6:7], v[224:225] op_sel_hi:[1,0,1]
	v_pk_fma_f32 v[8:9], v[8:9], v[6:7], v[222:223] op_sel_hi:[1,0,1]
	v_mul_f32_e32 v0, 0xbfb8aa3b, v20
	v_mul_f32_e32 v1, 0xbfb8aa3b, v21
	v_mul_f32_e32 v2, 0xbfb8aa3b, v22
	v_mul_f32_e32 v3, 0xbfb8aa3b, v23
	v_mul_f32_e32 v242, 0xbfb8aa3b, v16
	v_mul_f32_e32 v243, 0xbfb8aa3b, v17
	v_mul_f32_e32 v244, 0xbfb8aa3b, v18
	v_mul_f32_e32 v245, 0xbfb8aa3b, v19
	v_exp_f32_e32 v0, v0
	v_exp_f32_e32 v1, v1
	v_exp_f32_e32 v2, v2
	v_exp_f32_e32 v3, v3
	v_exp_f32_e32 v242, v242
	v_exp_f32_e32 v243, v243
	v_exp_f32_e32 v244, v244
	v_exp_f32_e32 v245, v245
	v_add_f32_e32 v0, 1.0, v0
	v_add_f32_e32 v1, 1.0, v1
	v_add_f32_e32 v2, 1.0, v2
	v_add_f32_e32 v3, 1.0, v3
	v_add_f32_e32 v242, 1.0, v242
	v_add_f32_e32 v243, 1.0, v243
	v_add_f32_e32 v244, 1.0, v244
	v_add_f32_e32 v245, 1.0, v245
	v_rcp_f32_e32 v0, v0
	v_rcp_f32_e32 v1, v1
	v_rcp_f32_e32 v2, v2
	v_rcp_f32_e32 v3, v3
	v_rcp_f32_e32 v242, v242
	v_rcp_f32_e32 v243, v243
	v_rcp_f32_e32 v244, v244
	v_rcp_f32_e32 v245, v245
	v_pk_mul_f32 v[20:21], v[20:21], v[0:1]
	v_pk_mul_f32 v[22:23], v[22:23], v[2:3]
	v_pk_mul_f32 v[16:17], v[16:17], v[242:243]
	v_pk_mul_f32 v[18:19], v[18:19], v[244:245]
	v_mul_f32_e32 v0, 0xbfb8aa3b, v12
	v_mul_f32_e32 v1, 0xbfb8aa3b, v13
	v_mul_f32_e32 v2, 0xbfb8aa3b, v14
	v_mul_f32_e32 v3, 0xbfb8aa3b, v15
	v_mul_f32_e32 v242, 0xbfb8aa3b, v8
	v_mul_f32_e32 v243, 0xbfb8aa3b, v9
	v_mul_f32_e32 v244, 0xbfb8aa3b, v10
	v_mul_f32_e32 v245, 0xbfb8aa3b, v11
	v_exp_f32_e32 v0, v0
	v_exp_f32_e32 v1, v1
	v_exp_f32_e32 v2, v2
	v_exp_f32_e32 v3, v3
	v_exp_f32_e32 v242, v242
	v_exp_f32_e32 v243, v243
	v_exp_f32_e32 v244, v244
	v_exp_f32_e32 v245, v245
	v_add_f32_e32 v0, 1.0, v0
	v_add_f32_e32 v1, 1.0, v1
	v_add_f32_e32 v2, 1.0, v2
	v_add_f32_e32 v3, 1.0, v3
	v_add_f32_e32 v242, 1.0, v242
	v_add_f32_e32 v243, 1.0, v243
	v_add_f32_e32 v244, 1.0, v244
	v_add_f32_e32 v245, 1.0, v245
	v_rcp_f32_e32 v0, v0
	v_rcp_f32_e32 v1, v1
	v_rcp_f32_e32 v2, v2
	v_rcp_f32_e32 v3, v3
	v_rcp_f32_e32 v242, v242
	v_rcp_f32_e32 v243, v243
	v_rcp_f32_e32 v244, v244
	v_rcp_f32_e32 v245, v245
	v_pk_mul_f32 v[12:13], v[12:13], v[0:1]
	v_pk_mul_f32 v[14:15], v[14:15], v[2:3]
	v_pk_mul_f32 v[8:9], v[8:9], v[242:243]
	v_pk_mul_f32 v[10:11], v[10:11], v[244:245]
	v_cvt_pk_bf16_f32 v234, v20, v21
	v_cvt_pk_bf16_f32 v235, v22, v23
	v_cvt_pk_bf16_f32 v236, v16, v17
	v_cvt_pk_bf16_f32 v237, v18, v19
	v_cvt_pk_bf16_f32 v238, v12, v13
	v_cvt_pk_bf16_f32 v239, v14, v15
	v_cvt_pk_bf16_f32 v240, v8, v9
	v_cvt_pk_bf16_f32 v241, v10, v11
	s_mov_b64 vcc, s[6:7]
	v_cndmask_b32_dpp v20, v238, v234, vcc row_ror:8 row_mask:0xf bank_mask:0xf
	v_cndmask_b32_dpp v21, v239, v235, vcc row_ror:8 row_mask:0xf bank_mask:0xf
	v_cndmask_b32_dpp v22, v240, v236, vcc row_ror:8 row_mask:0xf bank_mask:0xf
	v_cndmask_b32_dpp v23, v241, v237, vcc row_ror:8 row_mask:0xf bank_mask:0xf
	s_not_b64 vcc, s[6:7]
	v_cndmask_b32_dpp v16, v234, v238, vcc row_ror:8 row_mask:0xf bank_mask:0xf
	v_cndmask_b32_dpp v17, v235, v239, vcc row_ror:8 row_mask:0xf bank_mask:0xf
	v_cndmask_b32_dpp v18, v236, v240, vcc row_ror:8 row_mask:0xf bank_mask:0xf
	v_cndmask_b32_dpp v19, v237, v241, vcc row_ror:8 row_mask:0xf bank_mask:0xf
	global_store_dwordx4 v246, v[20:23], s[12:13]
	global_store_dwordx4 v247, v[16:19], s[12:13]
	s_mov_b32 s100, 1
	s_branch .LBB0_1422
.Lfn_plain:
	s_waitcnt vmcnt(4)
	v_mov_b32_e32 v6, v186
	v_pk_fma_f32 v[136:137], v[136:137], v[6:7], v[152:153] op_sel_hi:[1,0,1]
	v_pk_fma_f32 v[134:135], v[134:135], v[6:7], v[150:151] op_sel_hi:[1,0,1]
	v_pk_fma_f32 v[132:133], v[132:133], v[6:7], v[148:149] op_sel_hi:[1,0,1]
	v_pk_fma_f32 v[130:131], v[130:131], v[6:7], v[146:147] op_sel_hi:[1,0,1]
	v_pk_fma_f32 v[128:129], v[128:129], v[6:7], v[144:145] op_sel_hi:[1,0,1]
	v_pk_fma_f32 v[126:127], v[126:127], v[6:7], v[142:143] op_sel_hi:[1,0,1]
	v_pk_fma_f32 v[124:125], v[124:125], v[6:7], v[140:141] op_sel_hi:[1,0,1]
	v_pk_fma_f32 v[122:123], v[122:123], v[6:7], v[138:139] op_sel_hi:[1,0,1]
	v_cvt_pk_bf16_f32 v234, v134, v135
	v_cvt_pk_bf16_f32 v235, v136, v137
	v_cvt_pk_bf16_f32 v236, v130, v131
	v_cvt_pk_bf16_f32 v237, v132, v133
	v_cvt_pk_bf16_f32 v238, v126, v127
	v_cvt_pk_bf16_f32 v239, v128, v129
	v_cvt_pk_bf16_f32 v240, v122, v123
	v_cvt_pk_bf16_f32 v241, v124, v125
	s_mov_b64 vcc, s[6:7]
	v_cndmask_b32_dpp v134, v238, v234, vcc row_ror:8 row_mask:0xf bank_mask:0xf
	v_cndmask_b32_dpp v135, v239, v235, vcc row_ror:8 row_mask:0xf bank_mask:0xf
	v_cndmask_b32_dpp v136, v240, v236, vcc row_ror:8 row_mask:0xf bank_mask:0xf
	v_cndmask_b32_dpp v137, v241, v237, vcc row_ror:8 row_mask:0xf bank_mask:0xf
	s_not_b64 vcc, s[6:7]
	v_cndmask_b32_dpp v130, v234, v238, vcc row_ror:8 row_mask:0xf bank_mask:0xf
	v_cndmask_b32_dpp v131, v235, v239, vcc row_ror:8 row_mask:0xf bank_mask:0xf
	v_cndmask_b32_dpp v132, v236, v240, vcc row_ror:8 row_mask:0xf bank_mask:0xf
	v_cndmask_b32_dpp v133, v237, v241, vcc row_ror:8 row_mask:0xf bank_mask:0xf
	global_store_dwordx4 v246, v[134:137], s[12:13]
	global_store_dwordx4 v247, v[130:133], s[12:13]
	v_mov_b32_e32 v6, v187
	s_add_u32 s12, s12, 0x8000
	s_addc_u32 s13, s13, 0
	v_pk_fma_f32 v[120:121], v[120:121], v[6:7], v[152:153] op_sel_hi:[1,0,1]
	v_pk_fma_f32 v[118:119], v[118:119], v[6:7], v[150:151] op_sel_hi:[1,0,1]
	v_pk_fma_f32 v[116:117], v[116:117], v[6:7], v[148:149] op_sel_hi:[1,0,1]
	v_pk_fma_f32 v[114:115], v[114:115], v[6:7], v[146:147] op_sel_hi:[1,0,1]
	v_pk_fma_f32 v[112:113], v[112:113], v[6:7], v[144:145] op_sel_hi:[1,0,1]
	v_pk_fma_f32 v[110:111], v[110:111], v[6:7], v[142:143] op_sel_hi:[1,0,1]
	v_pk_fma_f32 v[108:109], v[108:109], v[6:7], v[140:141] op_sel_hi:[1,0,1]
	v_pk_fma_f32 v[106:107], v[106:107], v[6:7], v[138:139] op_sel_hi:[1,0,1]
	v_cvt_pk_bf16_f32 v234, v118, v119
	v_cvt_pk_bf16_f32 v235, v120, v121
	v_cvt_pk_bf16_f32 v236, v114, v115
	v_cvt_pk_bf16_f32 v237, v116, v117
	v_cvt_pk_bf16_f32 v238, v110, v111
	v_cvt_pk_bf16_f32 v239, v112, v113
	v_cvt_pk_bf16_f32 v240, v106, v107
	v_cvt_pk_bf16_f32 v241, v108, v109
	s_mov_b64 vcc, s[6:7]
	v_cndmask_b32_dpp v118, v238, v234, vcc row_ror:8 row_mask:0xf bank_mask:0xf
	v_cndmask_b32_dpp v119, v239, v235, vcc row_ror:8 row_mask:0xf bank_mask:0xf
	v_cndmask_b32_dpp v120, v240, v236, vcc row_ror:8 row_mask:0xf bank_mask:0xf
	v_cndmask_b32_dpp v121, v241, v237, vcc row_ror:8 row_mask:0xf bank_mask:0xf
	s_not_b64 vcc, s[6:7]
	v_cndmask_b32_dpp v114, v234, v238, vcc row_ror:8 row_mask:0xf bank_mask:0xf
	v_cndmask_b32_dpp v115, v235, v239, vcc row_ror:8 row_mask:0xf bank_mask:0xf
	v_cndmask_b32_dpp v116, v236, v240, vcc row_ror:8 row_mask:0xf bank_mask:0xf
	v_cndmask_b32_dpp v117, v237, v241, vcc row_ror:8 row_mask:0xf bank_mask:0xf
	global_store_dwordx4 v246, v[118:121], s[12:13]
	global_store_dwordx4 v247, v[114:117], s[12:13]
	s_add_u32 s10, s10, 0x9000
	s_addc_u32 s11, s11, 0
	global_load_dwordx4 v[150:153], v226, s[10:11]
	global_load_dwordx4 v[146:149], v226, s[10:11] offset:16
	global_load_dwordx4 v[142:145], v226, s[10:11] offset:128
	global_load_dwordx4 v[138:141], v226, s[10:11] offset:144
	s_waitcnt vmcnt(8)
	v_mov_b32_e32 v6, v188
	s_add_u32 s12, s12, 0x8000
	s_addc_u32 s13, s13, 0
	v_pk_fma_f32 v[104:105], v[104:105], v[6:7], v[196:197] op_sel_hi:[1,0,1]
	v_pk_fma_f32 v[102:103], v[102:103], v[6:7], v[194:195] op_sel_hi:[1,0,1]
	v_pk_fma_f32 v[100:101], v[100:101], v[6:7], v[200:201] op_sel_hi:[1,0,1]
	v_pk_fma_f32 v[98:99], v[98:99], v[6:7], v[198:199] op_sel_hi:[1,0,1]
	v_pk_fma_f32 v[94:95], v[94:95], v[6:7], v[204:205] op_sel_hi:[1,0,1]
	v_pk_fma_f32 v[92:93], v[92:93], v[6:7], v[202:203] op_sel_hi:[1,0,1]
	v_pk_fma_f32 v[90:91], v[90:91], v[6:7], v[224:225] op_sel_hi:[1,0,1]
	v_pk_fma_f32 v[88:89], v[88:89], v[6:7], v[222:223] op_sel_hi:[1,0,1]
	v_cvt_pk_bf16_f32 v234, v102, v103
	v_cvt_pk_bf16_f32 v235, v104, v105
	v_cvt_pk_bf16_f32 v236, v98, v99
	v_cvt_pk_bf16_f32 v237, v100, v101
	v_cvt_pk_bf16_f32 v238, v92, v93
	v_cvt_pk_bf16_f32 v239, v94, v95
	v_cvt_pk_bf16_f32 v240, v88, v89
	v_cvt_pk_bf16_f32 v241, v90, v91
	s_mov_b64 vcc, s[6:7]
	v_cndmask_b32_dpp v102, v238, v234, vcc row_ror:8 row_mask:0xf bank_mask:0xf
	v_cndmask_b32_dpp v103, v239, v235, vcc row_ror:8 row_mask:0xf bank_mask:0xf
	v_cndmask_b32_dpp v104, v240, v236, vcc row_ror:8 row_mask:0xf bank_mask:0xf
	v_cndmask_b32_dpp v105, v241, v237, vcc row_ror:8 row_mask:0xf bank_mask:0xf
	s_not_b64 vcc, s[6:7]
	v_cndmask_b32_dpp v98, v234, v238, vcc row_ror:8 row_mask:0xf bank_mask:0xf
	v_cndmask_b32_dpp v99, v235, v239, vcc row_ror:8 row_mask:0xf bank_mask:0xf
	v_cndmask_b32_dpp v100, v236, v240, vcc row_ror:8 row_mask:0xf bank_mask:0xf
	v_cndmask_b32_dpp v101, v237, v241, vcc row_ror:8 row_mask:0xf bank_mask:0xf
	global_store_dwordx4 v246, v[102:105], s[12:13]
	global_store_dwordx4 v247, v[98:101], s[12:13]
	v_mov_b32_e32 v6, v189
	s_add_u32 s12, s12, 0x8000
	s_addc_u32 s13, s13, 0
	v_pk_fma_f32 v[86:87], v[86:87], v[6:7], v[196:197] op_sel_hi:[1,0,1]
	v_pk_fma_f32 v[84:85], v[84:85], v[6:7], v[194:195] op_sel_hi:[1,0,1]
	v_pk_fma_f32 v[82:83], v[82:83], v[6:7], v[200:201] op_sel_hi:[1,0,1]
	v_pk_fma_f32 v[80:81], v[80:81], v[6:7], v[198:199] op_sel_hi:[1,0,1]
	v_pk_fma_f32 v[78:79], v[78:79], v[6:7], v[204:205] op_sel_hi:[1,0,1]
	v_pk_fma_f32 v[76:77], v[76:77], v[6:7], v[202:203] op_sel_hi:[1,0,1]
	v_pk_fma_f32 v[74:75], v[74:75], v[6:7], v[224:225] op_sel_hi:[1,0,1]
	v_pk_fma_f32 v[72:73], v[72:73], v[6:7], v[222:223] op_sel_hi:[1,0,1]
	v_cvt_pk_bf16_f32 v234, v84, v85
	v_cvt_pk_bf16_f32 v235, v86, v87
	v_cvt_pk_bf16_f32 v236, v80, v81
	v_cvt_pk_bf16_f32 v237, v82, v83
	v_cvt_pk_bf16_f32 v238, v76, v77
	v_cvt_pk_bf16_f32 v239, v78, v79
	v_cvt_pk_bf16_f32 v240, v72, v73
	v_cvt_pk_bf16_f32 v241, v74, v75
	s_mov_b64 vcc, s[6:7]
	v_cndmask_b32_dpp v84, v238, v234, vcc row_ror:8 row_mask:0xf bank_mask:0xf
	v_cndmask_b32_dpp v85, v239, v235, vcc row_ror:8 row_mask:0xf bank_mask:0xf
	v_cndmask_b32_dpp v86, v240, v236, vcc row_ror:8 row_mask:0xf bank_mask:0xf
	v_cndmask_b32_dpp v87, v241, v237, vcc row_ror:8 row_mask:0xf bank_mask:0xf
	s_not_b64 vcc, s[6:7]
	v_cndmask_b32_dpp v80, v234, v238, vcc row_ror:8 row_mask:0xf bank_mask:0xf
	v_cndmask_b32_dpp v81, v235, v239, vcc row_ror:8 row_mask:0xf bank_mask:0xf
	v_cndmask_b32_dpp v82, v236, v240, vcc row_ror:8 row_mask:0xf bank_mask:0xf
	v_cndmask_b32_dpp v83, v237, v241, vcc row_ror:8 row_mask:0xf bank_mask:0xf
	global_store_dwordx4 v246, v[84:87], s[12:13]
	global_store_dwordx4 v247, v[80:83], s[12:13]
	s_add_u32 s10, s10, 0x3000
	s_addc_u32 s11, s11, 0
	global_load_dwordx4 v[194:197], v226, s[10:11]
	global_load_dwordx4 v[198:201], v226, s[10:11] offset:16
	global_load_dwordx4 v[202:205], v226, s[10:11] offset:128
	global_load_dwordx4 v[222:225], v226, s[10:11] offset:144
	s_waitcnt vmcnt(8)
	v_mov_b32_e32 v6, v190
	s_add_u32 s12, s12, 0x28000
	s_addc_u32 s13, s13, 0
	v_pk_fma_f32 v[70:71], v[70:71], v[6:7], v[152:153] op_sel_hi:[1,0,1]
	v_pk_fma_f32 v[68:69], v[68:69], v[6:7], v[150:151] op_sel_hi:[1,0,1]
	v_pk_fma_f32 v[66:67], v[66:67], v[6:7], v[148:149] op_sel_hi:[1,0,1]
	v_pk_fma_f32 v[64:65], v[64:65], v[6:7], v[146:147] op_sel_hi:[1,0,1]
	v_pk_fma_f32 v[62:63], v[62:63], v[6:7], v[144:145] op_sel_hi:[1,0,1]
	v_pk_fma_f32 v[60:61], v[60:61], v[6:7], v[142:143] op_sel_hi:[1,0,1]
	v_pk_fma_f32 v[58:59], v[58:59], v[6:7], v[140:141] op_sel_hi:[1,0,1]
	v_pk_fma_f32 v[56:57], v[56:57], v[6:7], v[138:139] op_sel_hi:[1,0,1]
	v_cvt_pk_bf16_f32 v234, v68, v69
	v_cvt_pk_bf16_f32 v235, v70, v71
	v_cvt_pk_bf16_f32 v236, v64, v65
	v_cvt_pk_bf16_f32 v237, v66, v67
	v_cvt_pk_bf16_f32 v238, v60, v61
	v_cvt_pk_bf16_f32 v239, v62, v63
	v_cvt_pk_bf16_f32 v240, v56, v57
	v_cvt_pk_bf16_f32 v241, v58, v59
	s_mov_b64 vcc, s[6:7]
	v_cndmask_b32_dpp v68, v238, v234, vcc row_ror:8 row_mask:0xf bank_mask:0xf
	v_cndmask_b32_dpp v69, v239, v235, vcc row_ror:8 row_mask:0xf bank_mask:0xf
	v_cndmask_b32_dpp v70, v240, v236, vcc row_ror:8 row_mask:0xf bank_mask:0xf
	v_cndmask_b32_dpp v71, v241, v237, vcc row_ror:8 row_mask:0xf bank_mask:0xf
	s_not_b64 vcc, s[6:7]
	v_cndmask_b32_dpp v64, v234, v238, vcc row_ror:8 row_mask:0xf bank_mask:0xf
	v_cndmask_b32_dpp v65, v235, v239, vcc row_ror:8 row_mask:0xf bank_mask:0xf
	v_cndmask_b32_dpp v66, v236, v240, vcc row_ror:8 row_mask:0xf bank_mask:0xf
	v_cndmask_b32_dpp v67, v237, v241, vcc row_ror:8 row_mask:0xf bank_mask:0xf
	global_store_dwordx4 v246, v[68:71], s[12:13]
	global_store_dwordx4 v247, v[64:67], s[12:13]
	v_mov_b32_e32 v6, v191
	s_add_u32 s12, s12, 0x8000
	s_addc_u32 s13, s13, 0
	v_pk_fma_f32 v[54:55], v[54:55], v[6:7], v[152:153] op_sel_hi:[1,0,1]
	v_pk_fma_f32 v[52:53], v[52:53], v[6:7], v[150:151] op_sel_hi:[1,0,1]
	v_pk_fma_f32 v[50:51], v[50:51], v[6:7], v[148:149] op_sel_hi:[1,0,1]
	v_pk_fma_f32 v[48:49], v[48:49], v[6:7], v[146:147] op_sel_hi:[1,0,1]
	v_pk_fma_f32 v[46:47], v[46:47], v[6:7], v[144:145] op_sel_hi:[1,0,1]
	v_pk_fma_f32 v[44:45], v[44:45], v[6:7], v[142:143] op_sel_hi:[1,0,1]
	v_pk_fma_f32 v[42:43], v[42:43], v[6:7], v[140:141] op_sel_hi:[1,0,1]
	v_pk_fma_f32 v[40:41], v[40:41], v[6:7], v[138:139] op_sel_hi:[1,0,1]
	v_cvt_pk_bf16_f32 v234, v52, v53
	v_cvt_pk_bf16_f32 v235, v54, v55
	v_cvt_pk_bf16_f32 v236, v48, v49
	v_cvt_pk_bf16_f32 v237, v50, v51
	v_cvt_pk_bf16_f32 v238, v44, v45
	v_cvt_pk_bf16_f32 v239, v46, v47
	v_cvt_pk_bf16_f32 v240, v40, v41
	v_cvt_pk_bf16_f32 v241, v42, v43
	s_mov_b64 vcc, s[6:7]
	v_cndmask_b32_dpp v52, v238, v234, vcc row_ror:8 row_mask:0xf bank_mask:0xf
	v_cndmask_b32_dpp v53, v239, v235, vcc row_ror:8 row_mask:0xf bank_mask:0xf
	v_cndmask_b32_dpp v54, v240, v236, vcc row_ror:8 row_mask:0xf bank_mask:0xf
	v_cndmask_b32_dpp v55, v241, v237, vcc row_ror:8 row_mask:0xf bank_mask:0xf
	s_not_b64 vcc, s[6:7]
	v_cndmask_b32_dpp v48, v234, v238, vcc row_ror:8 row_mask:0xf bank_mask:0xf
	v_cndmask_b32_dpp v49, v235, v239, vcc row_ror:8 row_mask:0xf bank_mask:0xf
	v_cndmask_b32_dpp v50, v236, v240, vcc row_ror:8 row_mask:0xf bank_mask:0xf
	v_cndmask_b32_dpp v51, v237, v241, vcc row_ror:8 row_mask:0xf bank_mask:0xf
	global_store_dwordx4 v246, v[52:55], s[12:13]
	global_store_dwordx4 v247, v[48:51], s[12:13]
	s_waitcnt vmcnt(4)
	v_mov_b32_e32 v6, v192
	s_add_u32 s12, s12, 0x8000
	s_addc_u32 s13, s13, 0
	v_pk_fma_f32 v[38:39], v[38:39], v[6:7], v[196:197] op_sel_hi:[1,0,1]
	v_pk_fma_f32 v[36:37], v[36:37], v[6:7], v[194:195] op_sel_hi:[1,0,1]
	v_pk_fma_f32 v[34:35], v[34:35], v[6:7], v[200:201] op_sel_hi:[1,0,1]
	v_pk_fma_f32 v[32:33], v[32:33], v[6:7], v[198:199] op_sel_hi:[1,0,1]
	v_pk_fma_f32 v[30:31], v[30:31], v[6:7], v[204:205] op_sel_hi:[1,0,1]
	v_pk_fma_f32 v[28:29], v[28:29], v[6:7], v[202:203] op_sel_hi:[1,0,1]
	v_pk_fma_f32 v[26:27], v[26:27], v[6:7], v[224:225] op_sel_hi:[1,0,1]
	v_pk_fma_f32 v[24:25], v[24:25], v[6:7], v[222:223] op_sel_hi:[1,0,1]
	v_cvt_pk_bf16_f32 v234, v36, v37
	v_cvt_pk_bf16_f32 v235, v38, v39
	v_cvt_pk_bf16_f32 v236, v32, v33
	v_cvt_pk_bf16_f32 v237, v34, v35
	v_cvt_pk_bf16_f32 v238, v28, v29
	v_cvt_pk_bf16_f32 v239, v30, v31
	v_cvt_pk_bf16_f32 v240, v24, v25
	v_cvt_pk_bf16_f32 v241, v26, v27
	s_mov_b64 vcc, s[6:7]
	v_cndmask_b32_dpp v36, v238, v234, vcc row_ror:8 row_mask:0xf bank_mask:0xf
	v_cndmask_b32_dpp v37, v239, v235, vcc row_ror:8 row_mask:0xf bank_mask:0xf
	v_cndmask_b32_dpp v38, v240, v236, vcc row_ror:8 row_mask:0xf bank_mask:0xf
	v_cndmask_b32_dpp v39, v241, v237, vcc row_ror:8 row_mask:0xf bank_mask:0xf
	s_not_b64 vcc, s[6:7]
	v_cndmask_b32_dpp v32, v234, v238, vcc row_ror:8 row_mask:0xf bank_mask:0xf
	v_cndmask_b32_dpp v33, v235, v239, vcc row_ror:8 row_mask:0xf bank_mask:0xf
	v_cndmask_b32_dpp v34, v236, v240, vcc row_ror:8 row_mask:0xf bank_mask:0xf
	v_cndmask_b32_dpp v35, v237, v241, vcc row_ror:8 row_mask:0xf bank_mask:0xf
	global_store_dwordx4 v246, v[36:39], s[12:13]
	global_store_dwordx4 v247, v[32:35], s[12:13]
	v_mov_b32_e32 v6, v193
	s_add_u32 s12, s12, 0x8000
	s_addc_u32 s13, s13, 0
	v_pk_fma_f32 v[22:23], v[22:23], v[6:7], v[196:197] op_sel_hi:[1,0,1]
	v_pk_fma_f32 v[20:21], v[20:21], v[6:7], v[194:195] op_sel_hi:[1,0,1]
	v_pk_fma_f32 v[18:19], v[18:19], v[6:7], v[200:201] op_sel_hi:[1,0,1]
	v_pk_fma_f32 v[16:17], v[16:17], v[6:7], v[198:199] op_sel_hi:[1,0,1]
	v_pk_fma_f32 v[14:15], v[14:15], v[6:7], v[204:205] op_sel_hi:[1,0,1]
	v_pk_fma_f32 v[12:13], v[12:13], v[6:7], v[202:203] op_sel_hi:[1,0,1]
	v_pk_fma_f32 v[10:11], v[10:11], v[6:7], v[224:225] op_sel_hi:[1,0,1]
	v_pk_fma_f32 v[8:9], v[8:9], v[6:7], v[222:223] op_sel_hi:[1,0,1]
	v_cvt_pk_bf16_f32 v234, v20, v21
	v_cvt_pk_bf16_f32 v235, v22, v23
	v_cvt_pk_bf16_f32 v236, v16, v17
	v_cvt_pk_bf16_f32 v237, v18, v19
	v_cvt_pk_bf16_f32 v238, v12, v13
	v_cvt_pk_bf16_f32 v239, v14, v15
	v_cvt_pk_bf16_f32 v240, v8, v9
	v_cvt_pk_bf16_f32 v241, v10, v11
	s_mov_b64 vcc, s[6:7]
	v_cndmask_b32_dpp v20, v238, v234, vcc row_ror:8 row_mask:0xf bank_mask:0xf
	v_cndmask_b32_dpp v21, v239, v235, vcc row_ror:8 row_mask:0xf bank_mask:0xf
	v_cndmask_b32_dpp v22, v240, v236, vcc row_ror:8 row_mask:0xf bank_mask:0xf
	v_cndmask_b32_dpp v23, v241, v237, vcc row_ror:8 row_mask:0xf bank_mask:0xf
	s_not_b64 vcc, s[6:7]
	v_cndmask_b32_dpp v16, v234, v238, vcc row_ror:8 row_mask:0xf bank_mask:0xf
	v_cndmask_b32_dpp v17, v235, v239, vcc row_ror:8 row_mask:0xf bank_mask:0xf
	v_cndmask_b32_dpp v18, v236, v240, vcc row_ror:8 row_mask:0xf bank_mask:0xf
	v_cndmask_b32_dpp v19, v237, v241, vcc row_ror:8 row_mask:0xf bank_mask:0xf
	global_store_dwordx4 v246, v[20:23], s[12:13]
	global_store_dwordx4 v247, v[16:19], s[12:13]
	s_mov_b32 s100, 1
	s_branch .LBB0_1422
.Lfn_k234:
	s_cmp_eq_u32 s35, 4
	s_cbranch_scc1 .Lfn_k4
	v_lshl_add_u32 v246, v207, 9, v2
	v_add_u32_e32 v247, 0x1000, v246
	s_cmp_eq_u32 s35, 2
	s_cselect_b32 s12, s52, s54
	s_cselect_b32 s13, s53, s55
	s_lshl_b32 s18, s18, 9
	s_add_u32 s12, s12, s18
	s_addc_u32 s13, s13, 0
	s_cmp_eq_u32 s35, 2
	s_cselect_b32 s18, s84, s65
	s_cselect_b32 s19, s85, s66
	s_lshl_b32 s2, s16, 2
	s_lshl_b32 s2, s2, 10
	s_add_u32 s84, s18, s2
	s_addc_u32 s85, s19, 0
	s_add_u32 s84, s84, 0x18000
	s_addc_u32 s85, s85, 0
	s_waitcnt vmcnt(4)
	v_mov_b32_e32 v6, v186
	v_pk_fma_f32 v[136:137], v[136:137], v[6:7], v[152:153] op_sel_hi:[1,0,1]
	v_pk_fma_f32 v[134:135], v[134:135], v[6:7], v[150:151] op_sel_hi:[1,0,1]
	v_pk_fma_f32 v[132:133], v[132:133], v[6:7], v[148:149] op_sel_hi:[1,0,1]
	v_pk_fma_f32 v[130:131], v[130:131], v[6:7], v[146:147] op_sel_hi:[1,0,1]
	v_pk_fma_f32 v[128:129], v[128:129], v[6:7], v[144:145] op_sel_hi:[1,0,1]
	v_pk_fma_f32 v[126:127], v[126:127], v[6:7], v[142:143] op_sel_hi:[1,0,1]
	v_pk_fma_f32 v[124:125], v[124:125], v[6:7], v[140:141] op_sel_hi:[1,0,1]
	v_pk_fma_f32 v[122:123], v[122:123], v[6:7], v[138:139] op_sel_hi:[1,0,1]
	s_add_u32 s18, s84, 0
	s_addc_u32 s19, s85, 0
	global_store_dwordx4 v227, v[134:137], s[18:19]
	global_store_dwordx4 v227, v[130:133], s[18:19] offset:16
	global_store_dwordx4 v227, v[126:129], s[18:19] offset:128
	global_store_dwordx4 v227, v[122:125], s[18:19] offset:144
	v_cvt_pk_bf16_f32 v234, v134, v135
	v_cvt_pk_bf16_f32 v235, v136, v137
	v_cvt_pk_bf16_f32 v236, v130, v131
	v_cvt_pk_bf16_f32 v237, v132, v133
	v_cvt_pk_bf16_f32 v238, v126, v127
	v_cvt_pk_bf16_f32 v239, v128, v129
	v_cvt_pk_bf16_f32 v240, v122, v123
	v_cvt_pk_bf16_f32 v241, v124, v125
	s_mov_b64 vcc, s[6:7]
	v_cndmask_b32_dpp v134, v238, v234, vcc row_ror:8 row_mask:0xf bank_mask:0xf
	v_cndmask_b32_dpp v135, v239, v235, vcc row_ror:8 row_mask:0xf bank_mask:0xf
	v_cndmask_b32_dpp v136, v240, v236, vcc row_ror:8 row_mask:0xf bank_mask:0xf
	v_cndmask_b32_dpp v137, v241, v237, vcc row_ror:8 row_mask:0xf bank_mask:0xf
	s_not_b64 vcc, s[6:7]
	v_cndmask_b32_dpp v130, v234, v238, vcc row_ror:8 row_mask:0xf bank_mask:0xf
	v_cndmask_b32_dpp v131, v235, v239, vcc row_ror:8 row_mask:0xf bank_mask:0xf
	v_cndmask_b32_dpp v132, v236, v240, vcc row_ror:8 row_mask:0xf bank_mask:0xf
	v_cndmask_b32_dpp v133, v237, v241, vcc row_ror:8 row_mask:0xf bank_mask:0xf
	global_store_dwordx4 v246, v[134:137], s[12:13]
	global_store_dwordx4 v247, v[130:133], s[12:13]
	v_mov_b32_e32 v6, v187
	s_add_u32 s12, s12, 0x2000
	s_addc_u32 s13, s13, 0
	v_pk_fma_f32 v[120:121], v[120:121], v[6:7], v[152:153] op_sel_hi:[1,0,1]
	v_pk_fma_f32 v[118:119], v[118:119], v[6:7], v[150:151] op_sel_hi:[1,0,1]
	v_pk_fma_f32 v[116:117], v[116:117], v[6:7], v[148:149] op_sel_hi:[1,0,1]
	v_pk_fma_f32 v[114:115], v[114:115], v[6:7], v[146:147] op_sel_hi:[1,0,1]
	v_pk_fma_f32 v[112:113], v[112:113], v[6:7], v[144:145] op_sel_hi:[1,0,1]
	v_pk_fma_f32 v[110:111], v[110:111], v[6:7], v[142:143] op_sel_hi:[1,0,1]
	v_pk_fma_f32 v[108:109], v[108:109], v[6:7], v[140:141] op_sel_hi:[1,0,1]
	v_pk_fma_f32 v[106:107], v[106:107], v[6:7], v[138:139] op_sel_hi:[1,0,1]
	s_add_u32 s18, s84, 0x4000
	s_addc_u32 s19, s85, 0
	global_store_dwordx4 v227, v[118:121], s[18:19]
	global_store_dwordx4 v227, v[114:117], s[18:19] offset:16
	global_store_dwordx4 v227, v[110:113], s[18:19] offset:128
	global_store_dwordx4 v227, v[106:109], s[18:19] offset:144
	v_cvt_pk_bf16_f32 v234, v118, v119
	v_cvt_pk_bf16_f32 v235, v120, v121
	v_cvt_pk_bf16_f32 v236, v114, v115
	v_cvt_pk_bf16_f32 v237, v116, v117
	v_cvt_pk_bf16_f32 v238, v110, v111
	v_cvt_pk_bf16_f32 v239, v112, v113
	v_cvt_pk_bf16_f32 v240, v106, v107
	v_cvt_pk_bf16_f32 v241, v108, v109
	s_mov_b64 vcc, s[6:7]
	v_cndmask_b32_dpp v118, v238, v234, vcc row_ror:8 row_mask:0xf bank_mask:0xf
	v_cndmask_b32_dpp v119, v239, v235, vcc row_ror:8 row_mask:0xf bank_mask:0xf
	v_cndmask_b32_dpp v120, v240, v236, vcc row_ror:8 row_mask:0xf bank_mask:0xf
	v_cndmask_b32_dpp v121, v241, v237, vcc row_ror:8 row_mask:0xf bank_mask:0xf
	s_not_b64 vcc, s[6:7]
	v_cndmask_b32_dpp v114, v234, v238, vcc row_ror:8 row_mask:0xf bank_mask:0xf
	v_cndmask_b32_dpp v115, v235, v239, vcc row_ror:8 row_mask:0xf bank_mask:0xf
	v_cndmask_b32_dpp v116, v236, v240, vcc row_ror:8 row_mask:0xf bank_mask:0xf
	v_cndmask_b32_dpp v117, v237, v241, vcc row_ror:8 row_mask:0xf bank_mask:0xf
	global_store_dwordx4 v246, v[118:121], s[12:13]
	global_store_dwordx4 v247, v[114:117], s[12:13]
	s_add_u32 s10, s10, 0x9000
	s_addc_u32 s11, s11, 0
	global_load_dwordx4 v[150:153], v226, s[10:11]
	global_load_dwordx4 v[146:149], v226, s[10:11] offset:16
	global_load_dwordx4 v[142:145], v226, s[10:11] offset:128
	global_load_dwordx4 v[138:141], v226, s[10:11] offset:144
	s_waitcnt vmcnt(16)
	v_mov_b32_e32 v6, v188
	s_add_u32 s12, s12, 0x2000
	s_addc_u32 s13, s13, 0
	v_pk_fma_f32 v[104:105], v[104:105], v[6:7], v[196:197] op_sel_hi:[1,0,1]
	v_pk_fma_f32 v[102:103], v[102:103], v[6:7], v[194:195] op_sel_hi:[1,0,1]
	v_pk_fma_f32 v[100:101], v[100:101], v[6:7], v[200:201] op_sel_hi:[1,0,1]
	v_pk_fma_f32 v[98:99], v[98:99], v[6:7], v[198:199] op_sel_hi:[1,0,1]
	v_pk_fma_f32 v[94:95], v[94:95], v[6:7], v[204:205] op_sel_hi:[1,0,1]
	v_pk_fma_f32 v[92:93], v[92:93], v[6:7], v[202:203] op_sel_hi:[1,0,1]
	v_pk_fma_f32 v[90:91], v[90:91], v[6:7], v[224:225] op_sel_hi:[1,0,1]
	v_pk_fma_f32 v[88:89], v[88:89], v[6:7], v[222:223] op_sel_hi:[1,0,1]
	s_add_u32 s18, s84, 0x20000
	s_addc_u32 s19, s85, 0
	global_store_dwordx4 v227, v[102:105], s[18:19]
	global_store_dwordx4 v227, v[98:101], s[18:19] offset:16
	global_store_dwordx4 v227, v[92:95], s[18:19] offset:128
	global_store_dwordx4 v227, v[88:91], s[18:19] offset:144
	v_cvt_pk_bf16_f32 v234, v102, v103
	v_cvt_pk_bf16_f32 v235, v104, v105
	v_cvt_pk_bf16_f32 v236, v98, v99
	v_cvt_pk_bf16_f32 v237, v100, v101
	v_cvt_pk_bf16_f32 v238, v92, v93
	v_cvt_pk_bf16_f32 v239, v94, v95
	v_cvt_pk_bf16_f32 v240, v88, v89
	v_cvt_pk_bf16_f32 v241, v90, v91
	s_mov_b64 vcc, s[6:7]
	v_cndmask_b32_dpp v102, v238, v234, vcc row_ror:8 row_mask:0xf bank_mask:0xf
	v_cndmask_b32_dpp v103, v239, v235, vcc row_ror:8 row_mask:0xf bank_mask:0xf
	v_cndmask_b32_dpp v104, v240, v236, vcc row_ror:8 row_mask:0xf bank_mask:0xf
	v_cndmask_b32_dpp v105, v241, v237, vcc row_ror:8 row_mask:0xf bank_mask:0xf
	s_not_b64 vcc, s[6:7]
	v_cndmask_b32_dpp v98, v234, v238, vcc row_ror:8 row_mask:0xf bank_mask:0xf
	v_cndmask_b32_dpp v99, v235, v239, vcc row_ror:8 row_mask:0xf bank_mask:0xf
	v_cndmask_b32_dpp v100, v236, v240, vcc row_ror:8 row_mask:0xf bank_mask:0xf
	v_cndmask_b32_dpp v101, v237, v241, vcc row_ror:8 row_mask:0xf bank_mask:0xf
	global_store_dwordx4 v246, v[102:105], s[12:13]
	global_store_dwordx4 v247, v[98:101], s[12:13]
	v_mov_b32_e32 v6, v189
	s_add_u32 s12, s12, 0x2000
	s_addc_u32 s13, s13, 0
	v_pk_fma_f32 v[86:87], v[86:87], v[6:7], v[196:197] op_sel_hi:[1,0,1]
	v_pk_fma_f32 v[84:85], v[84:85], v[6:7], v[194:195] op_sel_hi:[1,0,1]
	v_pk_fma_f32 v[82:83], v[82:83], v[6:7], v[200:201] op_sel_hi:[1,0,1]
	v_pk_fma_f32 v[80:81], v[80:81], v[6:7], v[198:199] op_sel_hi:[1,0,1]
	v_pk_fma_f32 v[78:79], v[78:79], v[6:7], v[204:205] op_sel_hi:[1,0,1]
	v_pk_fma_f32 v[76:77], v[76:77], v[6:7], v[202:203] op_sel_hi:[1,0,1]
	v_pk_fma_f32 v[74:75], v[74:75], v[6:7], v[224:225] op_sel_hi:[1,0,1]
	v_pk_fma_f32 v[72:73], v[72:73], v[6:7], v[222:223] op_sel_hi:[1,0,1]
	s_add_u32 s18, s84, 0x24000
	s_addc_u32 s19, s85, 0
	global_store_dwordx4 v227, v[84:87], s[18:19]
	global_store_dwordx4 v227, v[80:83], s[18:19] offset:16
	global_store_dwordx4 v227, v[76:79], s[18:19] offset:128
	global_store_dwordx4 v227, v[72:75], s[18:19] offset:144
	v_cvt_pk_bf16_f32 v234, v84, v85
	v_cvt_pk_bf16_f32 v235, v86, v87
	v_cvt_pk_bf16_f32 v236, v80, v81
	v_cvt_pk_bf16_f32 v237, v82, v83
	v_cvt_pk_bf16_f32 v238, v76, v77
	v_cvt_pk_bf16_f32 v239, v78, v79
	v_cvt_pk_bf16_f32 v240, v72, v73
	v_cvt_pk_bf16_f32 v241, v74, v75
	s_mov_b64 vcc, s[6:7]
	v_cndmask_b32_dpp v84, v238, v234, vcc row_ror:8 row_mask:0xf bank_mask:0xf
	v_cndmask_b32_dpp v85, v239, v235, vcc row_ror:8 row_mask:0xf bank_mask:0xf
	v_cndmask_b32_dpp v86, v240, v236, vcc row_ror:8 row_mask:0xf bank_mask:0xf
	v_cndmask_b32_dpp v87, v241, v237, vcc row_ror:8 row_mask:0xf bank_mask:0xf
	s_not_b64 vcc, s[6:7]
	v_cndmask_b32_dpp v80, v234, v238, vcc row_ror:8 row_mask:0xf bank_mask:0xf
	v_cndmask_b32_dpp v81, v235, v239, vcc row_ror:8 row_mask:0xf bank_mask:0xf
	v_cndmask_b32_dpp v82, v236, v240, vcc row_ror:8 row_mask:0xf bank_mask:0xf
	v_cndmask_b32_dpp v83, v237, v241, vcc row_ror:8 row_mask:0xf bank_mask:0xf
	global_store_dwordx4 v246, v[84:87], s[12:13]
	global_store_dwordx4 v247, v[80:83], s[12:13]
	s_add_u32 s10, s10, 0x3000
	s_addc_u32 s11, s11, 0
	global_load_dwordx4 v[194:197], v226, s[10:11]
	global_load_dwordx4 v[198:201], v226, s[10:11] offset:16
	global_load_dwordx4 v[202:205], v226, s[10:11] offset:128
	global_load_dwordx4 v[222:225], v226, s[10:11] offset:144
	s_waitcnt vmcnt(16)
	v_mov_b32_e32 v6, v190
	s_add_u32 s12, s12, 0xa000
	s_addc_u32 s13, s13, 0
	v_pk_fma_f32 v[70:71], v[70:71], v[6:7], v[152:153] op_sel_hi:[1,0,1]
	v_pk_fma_f32 v[68:69], v[68:69], v[6:7], v[150:151] op_sel_hi:[1,0,1]
	v_pk_fma_f32 v[66:67], v[66:67], v[6:7], v[148:149] op_sel_hi:[1,0,1]
	v_pk_fma_f32 v[64:65], v[64:65], v[6:7], v[146:147] op_sel_hi:[1,0,1]
	v_pk_fma_f32 v[62:63], v[62:63], v[6:7], v[144:145] op_sel_hi:[1,0,1]
	v_pk_fma_f32 v[60:61], v[60:61], v[6:7], v[142:143] op_sel_hi:[1,0,1]
	v_pk_fma_f32 v[58:59], v[58:59], v[6:7], v[140:141] op_sel_hi:[1,0,1]
	v_pk_fma_f32 v[56:57], v[56:57], v[6:7], v[138:139] op_sel_hi:[1,0,1]
	s_add_u32 s18, s84, 0x80000
	s_addc_u32 s19, s85, 0
	global_store_dwordx4 v227, v[68:71], s[18:19]
	global_store_dwordx4 v227, v[64:67], s[18:19] offset:16
	global_store_dwordx4 v227, v[60:63], s[18:19] offset:128
	global_store_dwordx4 v227, v[56:59], s[18:19] offset:144
	v_cvt_pk_bf16_f32 v234, v68, v69
	v_cvt_pk_bf16_f32 v235, v70, v71
	v_cvt_pk_bf16_f32 v236, v64, v65
	v_cvt_pk_bf16_f32 v237, v66, v67
	v_cvt_pk_bf16_f32 v238, v60, v61
	v_cvt_pk_bf16_f32 v239, v62, v63
	v_cvt_pk_bf16_f32 v240, v56, v57
	v_cvt_pk_bf16_f32 v241, v58, v59
	s_mov_b64 vcc, s[6:7]
	v_cndmask_b32_dpp v68, v238, v234, vcc row_ror:8 row_mask:0xf bank_mask:0xf
	v_cndmask_b32_dpp v69, v239, v235, vcc row_ror:8 row_mask:0xf bank_mask:0xf
	v_cndmask_b32_dpp v70, v240, v236, vcc row_ror:8 row_mask:0xf bank_mask:0xf
	v_cndmask_b32_dpp v71, v241, v237, vcc row_ror:8 row_mask:0xf bank_mask:0xf
	s_not_b64 vcc, s[6:7]
	v_cndmask_b32_dpp v64, v234, v238, vcc row_ror:8 row_mask:0xf bank_mask:0xf
	v_cndmask_b32_dpp v65, v235, v239, vcc row_ror:8 row_mask:0xf bank_mask:0xf
	v_cndmask_b32_dpp v66, v236, v240, vcc row_ror:8 row_mask:0xf bank_mask:0xf
	v_cndmask_b32_dpp v67, v237, v241, vcc row_ror:8 row_mask:0xf bank_mask:0xf
	global_store_dwordx4 v246, v[68:71], s[12:13]
	global_store_dwordx4 v247, v[64:67], s[12:13]
	v_mov_b32_e32 v6, v191
	s_add_u32 s12, s12, 0x2000
	s_addc_u32 s13, s13, 0
	v_pk_fma_f32 v[54:55], v[54:55], v[6:7], v[152:153] op_sel_hi:[1,0,1]
	v_pk_fma_f32 v[52:53], v[52:53], v[6:7], v[150:151] op_sel_hi:[1,0,1]
	v_pk_fma_f32 v[50:51], v[50:51], v[6:7], v[148:149] op_sel_hi:[1,0,1]
	v_pk_fma_f32 v[48:49], v[48:49], v[6:7], v[146:147] op_sel_hi:[1,0,1]
	v_pk_fma_f32 v[46:47], v[46:47], v[6:7], v[144:145] op_sel_hi:[1,0,1]
	v_pk_fma_f32 v[44:45], v[44:45], v[6:7], v[142:143] op_sel_hi:[1,0,1]
	v_pk_fma_f32 v[42:43], v[42:43], v[6:7], v[140:141] op_sel_hi:[1,0,1]
	v_pk_fma_f32 v[40:41], v[40:41], v[6:7], v[138:139] op_sel_hi:[1,0,1]
	s_add_u32 s18, s84, 0x84000
	s_addc_u32 s19, s85, 0
	global_store_dwordx4 v227, v[52:55], s[18:19]
	global_store_dwordx4 v227, v[48:51], s[18:19] offset:16
	global_store_dwordx4 v227, v[44:47], s[18:19] offset:128
	global_store_dwordx4 v227, v[40:43], s[18:19] offset:144
	v_cvt_pk_bf16_f32 v234, v52, v53
	v_cvt_pk_bf16_f32 v235, v54, v55
	v_cvt_pk_bf16_f32 v236, v48, v49
	v_cvt_pk_bf16_f32 v237, v50, v51
	v_cvt_pk_bf16_f32 v238, v44, v45
	v_cvt_pk_bf16_f32 v239, v46, v47
	v_cvt_pk_bf16_f32 v240, v40, v41
	v_cvt_pk_bf16_f32 v241, v42, v43
	s_mov_b64 vcc, s[6:7]
	v_cndmask_b32_dpp v52, v238, v234, vcc row_ror:8 row_mask:0xf bank_mask:0xf
	v_cndmask_b32_dpp v53, v239, v235, vcc row_ror:8 row_mask:0xf bank_mask:0xf
	v_cndmask_b32_dpp v54, v240, v236, vcc row_ror:8 row_mask:0xf bank_mask:0xf
	v_cndmask_b32_dpp v55, v241, v237, vcc row_ror:8 row_mask:0xf bank_mask:0xf
	s_not_b64 vcc, s[6:7]
	v_cndmask_b32_dpp v48, v234, v238, vcc row_ror:8 row_mask:0xf bank_mask:0xf
	v_cndmask_b32_dpp v49, v235, v239, vcc row_ror:8 row_mask:0xf bank_mask:0xf
	v_cndmask_b32_dpp v50, v236, v240, vcc row_ror:8 row_mask:0xf bank_mask:0xf
	v_cndmask_b32_dpp v51, v237, v241, vcc row_ror:8 row_mask:0xf bank_mask:0xf
	global_store_dwordx4 v246, v[52:55], s[12:13]
	global_store_dwordx4 v247, v[48:51], s[12:13]
	s_waitcnt vmcnt(12)
	v_mov_b32_e32 v6, v192
	s_add_u32 s12, s12, 0x2000
	s_addc_u32 s13, s13, 0
	v_pk_fma_f32 v[38:39], v[38:39], v[6:7], v[196:197] op_sel_hi:[1,0,1]
	v_pk_fma_f32 v[36:37], v[36:37], v[6:7], v[194:195] op_sel_hi:[1,0,1]
	v_pk_fma_f32 v[34:35], v[34:35], v[6:7], v[200:201] op_sel_hi:[1,0,1]
	v_pk_fma_f32 v[32:33], v[32:33], v[6:7], v[198:199] op_sel_hi:[1,0,1]
	v_pk_fma_f32 v[30:31], v[30:31], v[6:7], v[204:205] op_sel_hi:[1,0,1]
	v_pk_fma_f32 v[28:29], v[28:29], v[6:7], v[202:203] op_sel_hi:[1,0,1]
	v_pk_fma_f32 v[26:27], v[26:27], v[6:7], v[224:225] op_sel_hi:[1,0,1]
	v_pk_fma_f32 v[24:25], v[24:25], v[6:7], v[222:223] op_sel_hi:[1,0,1]
	s_add_u32 s18, s84, 0xa0000
	s_addc_u32 s19, s85, 0
	global_store_dwordx4 v227, v[36:39], s[18:19]
	global_store_dwordx4 v227, v[32:35], s[18:19] offset:16
	global_store_dwordx4 v227, v[28:31], s[18:19] offset:128
	global_store_dwordx4 v227, v[24:27], s[18:19] offset:144
	v_cvt_pk_bf16_f32 v234, v36, v37
	v_cvt_pk_bf16_f32 v235, v38, v39
	v_cvt_pk_bf16_f32 v236, v32, v33
	v_cvt_pk_bf16_f32 v237, v34, v35
	v_cvt_pk_bf16_f32 v238, v28, v29
	v_cvt_pk_bf16_f32 v239, v30, v31
	v_cvt_pk_bf16_f32 v240, v24, v25
	v_cvt_pk_bf16_f32 v241, v26, v27
	s_mov_b64 vcc, s[6:7]
	v_cndmask_b32_dpp v36, v238, v234, vcc row_ror:8 row_mask:0xf bank_mask:0xf
	v_cndmask_b32_dpp v37, v239, v235, vcc row_ror:8 row_mask:0xf bank_mask:0xf
	v_cndmask_b32_dpp v38, v240, v236, vcc row_ror:8 row_mask:0xf bank_mask:0xf
	v_cndmask_b32_dpp v39, v241, v237, vcc row_ror:8 row_mask:0xf bank_mask:0xf
	s_not_b64 vcc, s[6:7]
	v_cndmask_b32_dpp v32, v234, v238, vcc row_ror:8 row_mask:0xf bank_mask:0xf
	v_cndmask_b32_dpp v33, v235, v239, vcc row_ror:8 row_mask:0xf bank_mask:0xf
	v_cndmask_b32_dpp v34, v236, v240, vcc row_ror:8 row_mask:0xf bank_mask:0xf
	v_cndmask_b32_dpp v35, v237, v241, vcc row_ror:8 row_mask:0xf bank_mask:0xf
	global_store_dwordx4 v246, v[36:39], s[12:13]
	global_store_dwordx4 v247, v[32:35], s[12:13]
	v_mov_b32_e32 v6, v193
	s_add_u32 s12, s12, 0x2000
	s_addc_u32 s13, s13, 0
	v_pk_fma_f32 v[22:23], v[22:23], v[6:7], v[196:197] op_sel_hi:[1,0,1]
	v_pk_fma_f32 v[20:21], v[20:21], v[6:7], v[194:195] op_sel_hi:[1,0,1]
	v_pk_fma_f32 v[18:19], v[18:19], v[6:7], v[200:201] op_sel_hi:[1,0,1]
	v_pk_fma_f32 v[16:17], v[16:17], v[6:7], v[198:199] op_sel_hi:[1,0,1]
	v_pk_fma_f32 v[14:15], v[14:15], v[6:7], v[204:205] op_sel_hi:[1,0,1]
	v_pk_fma_f32 v[12:13], v[12:13], v[6:7], v[202:203] op_sel_hi:[1,0,1]
	v_pk_fma_f32 v[10:11], v[10:11], v[6:7], v[224:225] op_sel_hi:[1,0,1]
	v_pk_fma_f32 v[8:9], v[8:9], v[6:7], v[222:223] op_sel_hi:[1,0,1]
	s_add_u32 s18, s84, 0xa4000
	s_addc_u32 s19, s85, 0
	global_store_dwordx4 v227, v[20:23], s[18:19]
	global_store_dwordx4 v227, v[16:19], s[18:19] offset:16
	global_store_dwordx4 v227, v[12:15], s[18:19] offset:128
	global_store_dwordx4 v227, v[8:11], s[18:19] offset:144
	v_cvt_pk_bf16_f32 v234, v20, v21
	v_cvt_pk_bf16_f32 v235, v22, v23
	v_cvt_pk_bf16_f32 v236, v16, v17
	v_cvt_pk_bf16_f32 v237, v18, v19
	v_cvt_pk_bf16_f32 v238, v12, v13
	v_cvt_pk_bf16_f32 v239, v14, v15
	v_cvt_pk_bf16_f32 v240, v8, v9
	v_cvt_pk_bf16_f32 v241, v10, v11
	s_mov_b64 vcc, s[6:7]
	v_cndmask_b32_dpp v20, v238, v234, vcc row_ror:8 row_mask:0xf bank_mask:0xf
	v_cndmask_b32_dpp v21, v239, v235, vcc row_ror:8 row_mask:0xf bank_mask:0xf
	v_cndmask_b32_dpp v22, v240, v236, vcc row_ror:8 row_mask:0xf bank_mask:0xf
	v_cndmask_b32_dpp v23, v241, v237, vcc row_ror:8 row_mask:0xf bank_mask:0xf
	s_not_b64 vcc, s[6:7]
	v_cndmask_b32_dpp v16, v234, v238, vcc row_ror:8 row_mask:0xf bank_mask:0xf
	v_cndmask_b32_dpp v17, v235, v239, vcc row_ror:8 row_mask:0xf bank_mask:0xf
	v_cndmask_b32_dpp v18, v236, v240, vcc row_ror:8 row_mask:0xf bank_mask:0xf
	v_cndmask_b32_dpp v19, v237, v241, vcc row_ror:8 row_mask:0xf bank_mask:0xf
	global_store_dwordx4 v246, v[20:23], s[12:13]
	global_store_dwordx4 v247, v[16:19], s[12:13]
	s_mov_b32 s100, 1
	s_branch .LBB0_1422
.Lfn_k4:
	v_cmp_lt_u32_e64 s[14:15], 0, v163
	s_lshr_b32 s16, s16, 5
	s_mul_i32 s16, s16, 0xf000
	s_waitcnt vmcnt(4)
	v_mov_b32_e32 v6, v187
	v_pk_fma_f32 v[120:121], v[120:121], v[6:7], v[152:153] op_sel_hi:[1,0,1]
	v_pk_fma_f32 v[118:119], v[118:119], v[6:7], v[150:151] op_sel_hi:[1,0,1]
	v_pk_fma_f32 v[116:117], v[116:117], v[6:7], v[148:149] op_sel_hi:[1,0,1]
	v_pk_fma_f32 v[114:115], v[114:115], v[6:7], v[146:147] op_sel_hi:[1,0,1]
	v_pk_fma_f32 v[112:113], v[112:113], v[6:7], v[144:145] op_sel_hi:[1,0,1]
	v_pk_fma_f32 v[110:111], v[110:111], v[6:7], v[142:143] op_sel_hi:[1,0,1]
	v_pk_fma_f32 v[108:109], v[108:109], v[6:7], v[140:141] op_sel_hi:[1,0,1]
	v_pk_fma_f32 v[106:107], v[106:107], v[6:7], v[138:139] op_sel_hi:[1,0,1]
	s_add_u32 s18, s46, 0
	s_addc_u32 s19, s47, 0
	s_add_u32 s18, s18, s16
	s_addc_u32 s19, s19, 0
	s_mov_b64 exec, s[14:15]
	global_store_dwordx4 v228, v[118:121], s[18:19]
	global_store_dwordx4 v228, v[114:117], s[18:19] offset:16
	global_store_dwordx4 v228, v[110:113], s[18:19] offset:128
	global_store_dwordx4 v228, v[106:109], s[18:19] offset:144
	s_mov_b64 exec, -1
	s_add_u32 s10, s10, 0x9000
	s_addc_u32 s11, s11, 0
	global_load_dwordx4 v[150:153], v226, s[10:11]
	global_load_dwordx4 v[146:149], v226, s[10:11] offset:16
	global_load_dwordx4 v[142:145], v226, s[10:11] offset:128
	global_load_dwordx4 v[138:141], v226, s[10:11] offset:144
	s_waitcnt vmcnt(8)
	v_mov_b32_e32 v6, v189
	v_pk_fma_f32 v[86:87], v[86:87], v[6:7], v[196:197] op_sel_hi:[1,0,1]
	v_pk_fma_f32 v[84:85], v[84:85], v[6:7], v[194:195] op_sel_hi:[1,0,1]
	v_pk_fma_f32 v[82:83], v[82:83], v[6:7], v[200:201] op_sel_hi:[1,0,1]
	v_pk_fma_f32 v[80:81], v[80:81], v[6:7], v[198:199] op_sel_hi:[1,0,1]
	v_pk_fma_f32 v[78:79], v[78:79], v[6:7], v[204:205] op_sel_hi:[1,0,1]
	v_pk_fma_f32 v[76:77], v[76:77], v[6:7], v[202:203] op_sel_hi:[1,0,1]
	v_pk_fma_f32 v[74:75], v[74:75], v[6:7], v[224:225] op_sel_hi:[1,0,1]
	v_pk_fma_f32 v[72:73], v[72:73], v[6:7], v[222:223] op_sel_hi:[1,0,1]
	s_add_u32 s18, s46, 0xf000
	s_addc_u32 s19, s47, 0
	s_add_u32 s18, s18, s16
	s_addc_u32 s19, s19, 0
	s_mov_b64 exec, s[14:15]
	global_store_dwordx4 v228, v[84:87], s[18:19]
	global_store_dwordx4 v228, v[80:83], s[18:19] offset:16
	global_store_dwordx4 v228, v[76:79], s[18:19] offset:128
	global_store_dwordx4 v228, v[72:75], s[18:19] offset:144
	s_mov_b64 exec, -1
	s_add_u32 s10, s10, 0x3000
	s_addc_u32 s11, s11, 0
	global_load_dwordx4 v[194:197], v226, s[10:11]
	global_load_dwordx4 v[198:201], v226, s[10:11] offset:16
	global_load_dwordx4 v[202:205], v226, s[10:11] offset:128
	global_load_dwordx4 v[222:225], v226, s[10:11] offset:144
	s_waitcnt vmcnt(8)
	v_mov_b32_e32 v6, v191
	v_pk_fma_f32 v[54:55], v[54:55], v[6:7], v[152:153] op_sel_hi:[1,0,1]
	v_pk_fma_f32 v[52:53], v[52:53], v[6:7], v[150:151] op_sel_hi:[1,0,1]
	v_pk_fma_f32 v[50:51], v[50:51], v[6:7], v[148:149] op_sel_hi:[1,0,1]
	v_pk_fma_f32 v[48:49], v[48:49], v[6:7], v[146:147] op_sel_hi:[1,0,1]
	v_pk_fma_f32 v[46:47], v[46:47], v[6:7], v[144:145] op_sel_hi:[1,0,1]
	v_pk_fma_f32 v[44:45], v[44:45], v[6:7], v[142:143] op_sel_hi:[1,0,1]
	v_pk_fma_f32 v[42:43], v[42:43], v[6:7], v[140:141] op_sel_hi:[1,0,1]
	v_pk_fma_f32 v[40:41], v[40:41], v[6:7], v[138:139] op_sel_hi:[1,0,1]
	s_add_u32 s18, s46, 0x3c000
	s_addc_u32 s19, s47, 0
	s_add_u32 s18, s18, s16
	s_addc_u32 s19, s19, 0
	s_mov_b64 exec, s[14:15]
	global_store_dwordx4 v228, v[52:55], s[18:19]
	global_store_dwordx4 v228, v[48:51], s[18:19] offset:16
	global_store_dwordx4 v228, v[44:47], s[18:19] offset:128
	global_store_dwordx4 v228, v[40:43], s[18:19] offset:144
	s_mov_b64 exec, -1
	s_waitcnt vmcnt(4)
	v_mov_b32_e32 v6, v193
	v_pk_fma_f32 v[22:23], v[22:23], v[6:7], v[196:197] op_sel_hi:[1,0,1]
	v_pk_fma_f32 v[20:21], v[20:21], v[6:7], v[194:195] op_sel_hi:[1,0,1]
	v_pk_fma_f32 v[18:19], v[18:19], v[6:7], v[200:201] op_sel_hi:[1,0,1]
	v_pk_fma_f32 v[16:17], v[16:17], v[6:7], v[198:199] op_sel_hi:[1,0,1]
	v_pk_fma_f32 v[14:15], v[14:15], v[6:7], v[204:205] op_sel_hi:[1,0,1]
	v_pk_fma_f32 v[12:13], v[12:13], v[6:7], v[202:203] op_sel_hi:[1,0,1]
	v_pk_fma_f32 v[10:11], v[10:11], v[6:7], v[224:225] op_sel_hi:[1,0,1]
	v_pk_fma_f32 v[8:9], v[8:9], v[6:7], v[222:223] op_sel_hi:[1,0,1]
	s_add_u32 s18, s46, 0x4b000
	s_addc_u32 s19, s47, 0
	s_add_u32 s18, s18, s16
	s_addc_u32 s19, s19, 0
	s_mov_b64 exec, s[14:15]
	global_store_dwordx4 v228, v[20:23], s[18:19]
	global_store_dwordx4 v228, v[16:19], s[18:19] offset:16
	global_store_dwordx4 v228, v[12:15], s[18:19] offset:128
	global_store_dwordx4 v228, v[8:11], s[18:19] offset:144
	s_mov_b64 exec, -1
	s_branch .LBB0_1422
